# v21 + nt cache policy on the once-read f32 weight loads of the conversion code (P0 and the five tail slots): the stream no longer displaces GEMM panels in L2 / Infinity Cache
# speedup vs baseline: 1.0115x; 1.0020x over previous
; #define LAS __attribute__((address_space(3)))
; __device__ __forceinline__ TrItem p0_item_of(const Params& p, int it, int lane) {
;     ...
;     const int nblk = N / 64, kb = r / nblk, nb = r % nblk, k0 = 64 * kb, n0 = 64 * nb;
;     TrItem t; t.src = W + (size_t)k0 * N + srccol(map, n0 + lane); t.N = N; t.K = K; t.fp8 = f8;
;     t.dst = f8 ? (bf16*)((unsigned char*)WT + (size_t)n0 * K + k0) : WT + (size_t)n0 * K + k0; return t;
; }
; __device__ __forceinline__ void tr_range(const Params& p, LAS unsigned char* lds, int first, int stride, int end, int lane, int wave) {
;     LAS float* scr = (LAS float*)(lds + wave * (64 * 65 * 4));
;     if (first >= end) return;
;     float ra[64];
;     TrItem cur = p0_item_of(p, first, lane);
; #pragma unroll
;     for (int i = 0; i < 64; ++i) ra[i] = cur.src[(size_t)i * cur.N];
.LBB0_5:
	s_or_b64 exec, exec, s[2:3]
	s_cmp_lt_i32 s90, 1
	s_cselect_b64 s[2:3], -1, 0
	s_cmp_gt_i32 s91, 0
	s_cselect_b64 s[4:5], -1, 0
	s_and_b64 s[4:5], s[2:3], s[4:5]
	s_andn2_b64 vcc, exec, s[4:5]
	v_and_b32_e32 v1, 63, v0
	s_cbranch_vccnz .LBB0_92
	s_lshr_b32 s10, s6, 6
	s_lshl_b32 s2, s86, 3
	s_add_i32 s11, s10, s2
	s_cmpk_gt_i32 s11, 0x15ff
	s_cbranch_scc1 .LBB0_11
	s_mul_i32 s2, s10, 0x4100
	s_lshl_b32 s12, s97, 3
	s_add_i32 s8, s2, 0
	s_add_u32 s13, s88, 0x400000
	s_mul_hi_i32 s2, s11, 0x2e8ba2e9
	s_addc_u32 s14, s89, 0
	s_lshr_b32 s3, s2, 31
	s_ashr_i32 s2, s2, 5
	s_add_i32 s3, s2, s3
	s_mul_i32 s2, s3, 0xb0
	s_sub_i32 s6, s11, s2
	s_lshl_b32 s2, s6, 6
	s_bfe_i32 s9, s6, 0x10001
	s_lshl_b32 s6, s6, 5
	s_and_b32 s9, s9, 0x1600
	s_and_b32 s6, s6, 0xffffff80
	s_load_dwordx16 s[16:31], s[0:1], 0x0
	s_and_b32 s7, s2, 64
	s_add_i32 s9, s9, s6
	s_or_b32 s6, s9, s7
	v_or_b32_e32 v2, s6, v1
	s_lshl_b32 s6, s3, 6
	s_ashr_i32 s7, s6, 31
	s_mul_i32 s3, s3, 0x2c0000
	s_mul_hi_i32 s9, s6, 0xb000
	s_waitcnt lgkmcnt(0)
	s_add_u32 s16, s30, s3
	s_addc_u32 s17, s31, s9
	v_ashrrev_i32_e32 v3, 31, v2
	v_lshl_add_u64 v[2:3], v[2:3], 2, s[16:17]
	s_mov_b32 s3, 0x2b5000
	v_add_co_u32_e32 v4, vcc, s3, v2
	s_mov_b32 s3, 0x2aa000
	s_nop 0
	v_addc_co_u32_e32 v5, vcc, 0, v3, vcc
	v_add_co_u32_e32 v6, vcc, s3, v2
	s_mov_b32 s3, 0x29f000
	s_nop 0
	v_addc_co_u32_e32 v7, vcc, 0, v3, vcc
	v_add_co_u32_e32 v8, vcc, s3, v2
	s_mov_b32 s3, 0x294000
	s_nop 0
	v_addc_co_u32_e32 v9, vcc, 0, v3, vcc
	v_add_co_u32_e32 v10, vcc, s3, v2
	s_mov_b32 s3, 0x289000
	s_nop 0
	v_addc_co_u32_e32 v11, vcc, 0, v3, vcc
	v_add_co_u32_e32 v12, vcc, s3, v2
	s_mov_b32 s3, 0x27e000
	s_nop 0
	v_addc_co_u32_e32 v13, vcc, 0, v3, vcc
	v_add_co_u32_e32 v14, vcc, s3, v2
	s_mov_b32 s3, 0x268000
	s_nop 0
	v_addc_co_u32_e32 v15, vcc, 0, v3, vcc
	v_add_co_u32_e32 v16, vcc, s3, v2
	s_mov_b32 s3, 0x25d000
	s_nop 0
	v_addc_co_u32_e32 v17, vcc, 0, v3, vcc
	v_add_co_u32_e32 v18, vcc, s3, v2
	s_mov_b32 s3, 0x252000
	s_nop 0
	v_addc_co_u32_e32 v19, vcc, 0, v3, vcc
	v_add_co_u32_e32 v22, vcc, s3, v2
	s_mov_b32 s3, 0x247000
	s_nop 0
	v_addc_co_u32_e32 v23, vcc, 0, v3, vcc
	v_add_co_u32_e32 v26, vcc, s3, v2
	s_mov_b32 s3, 0x23c000
	s_nop 0
	v_addc_co_u32_e32 v27, vcc, 0, v3, vcc
	v_add_co_u32_e32 v28, vcc, s3, v2
	s_mov_b32 s3, 0x231000
	s_nop 0
	v_addc_co_u32_e32 v29, vcc, 0, v3, vcc
	v_add_co_u32_e32 v30, vcc, s3, v2
	s_mov_b32 s3, 0x226000
	s_nop 0
	v_addc_co_u32_e32 v31, vcc, 0, v3, vcc
	v_add_co_u32_e32 v32, vcc, s3, v2
	s_mov_b32 s3, 0x21b000
	s_nop 0
	v_addc_co_u32_e32 v33, vcc, 0, v3, vcc
	v_add_co_u32_e32 v34, vcc, s3, v2
	s_mov_b32 s3, 0x210000
	s_nop 0
	v_addc_co_u32_e32 v35, vcc, 0, v3, vcc
	global_load_dword v20, v[16:17], off nt
	global_load_dword v49, v[18:19], off nt
	global_load_dword v24, v[22:23], off nt
	global_load_dword v25, v[26:27], off nt
	s_nop 0
	global_load_dword v26, v[28:29], off nt
	global_load_dword v27, v[30:31], off nt
	s_nop 0
	global_load_dword v28, v[32:33], off nt
	global_load_dword v50, v[34:35], off nt
	v_add_co_u32_e32 v16, vcc, s3, v2
	s_mov_b32 s3, 0x205000
	s_nop 0
	v_addc_co_u32_e32 v17, vcc, 0, v3, vcc
	v_add_co_u32_e32 v18, vcc, s3, v2
	s_mov_b32 s3, 0x1fa000
	s_nop 0
	v_addc_co_u32_e32 v19, vcc, 0, v3, vcc
	v_add_co_u32_e32 v22, vcc, s3, v2
	s_mov_b32 s3, 0x1ef000
	s_nop 0
	v_addc_co_u32_e32 v23, vcc, 0, v3, vcc
	v_add_co_u32_e32 v30, vcc, s3, v2
	s_mov_b32 s3, 0x1e4000
	s_nop 0
	v_addc_co_u32_e32 v31, vcc, 0, v3, vcc
	v_add_co_u32_e32 v32, vcc, s3, v2
	s_mov_b32 s3, 0x1d9000
	s_nop 0
	v_addc_co_u32_e32 v33, vcc, 0, v3, vcc
	v_add_co_u32_e32 v34, vcc, s3, v2
	s_mov_b32 s3, 0x1ce000
	s_nop 0
	v_addc_co_u32_e32 v35, vcc, 0, v3, vcc
	v_add_co_u32_e32 v36, vcc, s3, v2
	s_mov_b32 s3, 0x1c3000
	s_nop 0
	v_addc_co_u32_e32 v37, vcc, 0, v3, vcc
	v_add_co_u32_e32 v38, vcc, s3, v2
	s_mov_b32 s3, 0x1b8000
	s_nop 0
	v_addc_co_u32_e32 v39, vcc, 0, v3, vcc
	global_load_dword v74, v[16:17], off nt
	global_load_dword v51, v[18:19], off nt
	global_load_dword v29, v[22:23], off nt
	s_nop 0
	global_load_dword v30, v[30:31], off nt
	s_nop 0
	global_load_dword v31, v[32:33], off nt
	s_nop 0
	global_load_dword v32, v[34:35], off nt
	global_load_dword v33, v[36:37], off nt
	global_load_dword v52, v[38:39], off nt
	v_add_co_u32_e32 v16, vcc, s3, v2
	s_mov_b32 s3, 0x1ad000
	s_nop 0
	v_addc_co_u32_e32 v17, vcc, 0, v3, vcc
	v_add_co_u32_e32 v18, vcc, s3, v2
	s_mov_b32 s3, 0x1a2000
	s_nop 0
	v_addc_co_u32_e32 v19, vcc, 0, v3, vcc
	v_add_co_u32_e32 v22, vcc, s3, v2
	s_mov_b32 s3, 0x197000
	s_nop 0
	v_addc_co_u32_e32 v23, vcc, 0, v3, vcc
	v_add_co_u32_e32 v36, vcc, s3, v2
	s_mov_b32 s3, 0x18c000
	s_nop 0
	v_addc_co_u32_e32 v37, vcc, 0, v3, vcc
	v_add_co_u32_e32 v38, vcc, s3, v2
	s_mov_b32 s3, 0x181000
	s_nop 0
	v_addc_co_u32_e32 v39, vcc, 0, v3, vcc
	v_add_co_u32_e32 v40, vcc, s3, v2
	s_mov_b32 s3, 0x176000
	s_nop 0
	v_addc_co_u32_e32 v41, vcc, 0, v3, vcc
	v_add_co_u32_e32 v42, vcc, s3, v2
	s_mov_b32 s3, 0x16b000
	s_nop 0
	v_addc_co_u32_e32 v43, vcc, 0, v3, vcc
	v_add_co_u32_e32 v44, vcc, s3, v2
	s_mov_b32 s3, 0x160000
	s_nop 0
	v_addc_co_u32_e32 v45, vcc, 0, v3, vcc
	global_load_dword v75, v[16:17], off nt
	global_load_dword v53, v[18:19], off nt
	global_load_dword v34, v[22:23], off nt
	global_load_dword v35, v[36:37], off nt
	s_nop 0
	global_load_dword v36, v[38:39], off nt
	global_load_dword v37, v[40:41], off nt
	s_nop 0
	global_load_dword v38, v[42:43], off nt
	global_load_dword v54, v[44:45], off nt
	v_add_co_u32_e32 v16, vcc, s3, v2
	s_mov_b32 s3, 0x155000
	s_nop 0
	v_addc_co_u32_e32 v17, vcc, 0, v3, vcc
	v_add_co_u32_e32 v18, vcc, s3, v2
	s_mov_b32 s3, 0x14a000
	s_nop 0
; #define LAS __attribute__((address_space(3)))
; __device__ __forceinline__ void tr_range(const Params& p, LAS unsigned char* lds, int first, int stride, int end, int lane, int wave) {
;     LAS float* scr = (LAS float*)(lds + wave * (64 * 65 * 4));
;     if (first >= end) return;
;     float ra[64];
;     TrItem cur = p0_item_of(p, first, lane);
; #pragma unroll
;     for (int i = 0; i < 64; ++i) ra[i] = cur.src[(size_t)i * cur.N];
; #pragma unroll 1
;     for (int it = first; it < end; it += stride) {
; #pragma unroll
;         for (int i = 0; i < 64; ++i) scr[i * 65 + lane] = ra[i];
;         const bool more = it + stride < end;
;         TrItem nxt = cur;
;         if (more) { nxt = p0_item_of(p, it + stride, lane);
; #pragma unroll
;             for (int i = 0; i < 64; ++i) ra[i] = nxt.src[(size_t)i * nxt.N]; }
	v_addc_co_u32_e32 v19, vcc, 0, v3, vcc
	v_add_co_u32_e32 v22, vcc, s3, v2
	s_mov_b32 s3, 0x13f000
	s_nop 0
	v_addc_co_u32_e32 v23, vcc, 0, v3, vcc
	v_add_co_u32_e32 v40, vcc, s3, v2
	s_mov_b32 s3, 0x134000
	s_nop 0
	v_addc_co_u32_e32 v41, vcc, 0, v3, vcc
	v_add_co_u32_e32 v42, vcc, s3, v2
	s_mov_b32 s3, 0x129000
	s_nop 0
	v_addc_co_u32_e32 v43, vcc, 0, v3, vcc
	v_add_co_u32_e32 v44, vcc, s3, v2
	s_mov_b32 s3, 0x11e000
	s_nop 0
	v_addc_co_u32_e32 v45, vcc, 0, v3, vcc
	v_add_co_u32_e32 v46, vcc, s3, v2
	s_mov_b32 s3, 0x113000
	s_nop 0
	v_addc_co_u32_e32 v47, vcc, 0, v3, vcc
	v_add_co_u32_e32 v56, vcc, s3, v2
	s_mov_b32 s3, 0x108000
	s_nop 0
	v_addc_co_u32_e32 v57, vcc, 0, v3, vcc
	global_load_dword v76, v[16:17], off nt
	global_load_dword v55, v[18:19], off nt
	global_load_dword v39, v[22:23], off nt
	s_nop 0
	global_load_dword v40, v[40:41], off nt
	s_nop 0
	global_load_dword v41, v[42:43], off nt
	s_nop 0
	global_load_dword v42, v[44:45], off nt
	global_load_dword v43, v[46:47], off nt
	s_nop 0
	global_load_dword v56, v[56:57], off nt
	v_add_co_u32_e32 v16, vcc, s3, v2
	s_mov_b32 s3, 0xfd000
	s_nop 0
	v_addc_co_u32_e32 v17, vcc, 0, v3, vcc
	v_add_co_u32_e32 v18, vcc, s3, v2
	s_mov_b32 s3, 0xf2000
	s_nop 0
	v_addc_co_u32_e32 v19, vcc, 0, v3, vcc
	v_add_co_u32_e32 v22, vcc, s3, v2
	s_mov_b32 s3, 0xe7000
	s_nop 0
	v_addc_co_u32_e32 v23, vcc, 0, v3, vcc
	v_add_co_u32_e32 v46, vcc, s3, v2
	s_mov_b32 s3, 0xdc000
	s_nop 0
	v_addc_co_u32_e32 v47, vcc, 0, v3, vcc
	v_add_co_u32_e32 v58, vcc, s3, v2
	s_mov_b32 s3, 0xd1000
	s_nop 0
	v_addc_co_u32_e32 v59, vcc, 0, v3, vcc
	v_add_co_u32_e32 v60, vcc, s3, v2
	s_mov_b32 s3, 0xc6000
	s_nop 0
	v_addc_co_u32_e32 v61, vcc, 0, v3, vcc
	v_add_co_u32_e32 v62, vcc, s3, v2
	s_mov_b32 s3, 0xbb000
	s_nop 0
	v_addc_co_u32_e32 v63, vcc, 0, v3, vcc
	v_add_co_u32_e32 v64, vcc, s3, v2
	s_mov_b32 s3, 0xb0000
	s_nop 0
	v_addc_co_u32_e32 v65, vcc, 0, v3, vcc
	global_load_dword v77, v[16:17], off nt
	global_load_dword v57, v[18:19], off nt
	global_load_dword v44, v[22:23], off nt
	global_load_dword v45, v[46:47], off nt
	s_nop 0
	global_load_dword v46, v[58:59], off nt
	global_load_dword v47, v[60:61], off nt
	global_load_dword v48, v[62:63], off nt
	s_nop 0
	global_load_dword v58, v[64:65], off nt
	v_add_co_u32_e32 v16, vcc, s3, v2
	s_mov_b32 s3, 0xa5000
	s_nop 0
	v_addc_co_u32_e32 v17, vcc, 0, v3, vcc
	v_add_co_u32_e32 v18, vcc, s3, v2
	s_mov_b32 s3, 0x9a000
	s_nop 0
	v_addc_co_u32_e32 v19, vcc, 0, v3, vcc
	v_add_co_u32_e32 v22, vcc, s3, v2
	s_mov_b32 s3, 0x8f000
	s_nop 0
	v_addc_co_u32_e32 v23, vcc, 0, v3, vcc
	v_add_co_u32_e32 v60, vcc, s3, v2
	s_mov_b32 s3, 0x84000
	s_nop 0
	v_addc_co_u32_e32 v61, vcc, 0, v3, vcc
	v_add_co_u32_e32 v62, vcc, s3, v2
	s_mov_b32 s3, 0x79000
	s_nop 0
	v_addc_co_u32_e32 v63, vcc, 0, v3, vcc
	v_add_co_u32_e32 v64, vcc, s3, v2
	s_mov_b32 s3, 0x6e000
	s_nop 0
	v_addc_co_u32_e32 v65, vcc, 0, v3, vcc
	v_add_co_u32_e32 v66, vcc, s3, v2
	s_mov_b32 s3, 0x63000
	s_nop 0
	v_addc_co_u32_e32 v67, vcc, 0, v3, vcc
	v_add_co_u32_e32 v70, vcc, s3, v2
	s_mov_b32 s3, 0x58000
	s_nop 0
	v_addc_co_u32_e32 v71, vcc, 0, v3, vcc
	global_load_dword v78, v[16:17], off nt
	global_load_dword v69, v[18:19], off nt
	global_load_dword v59, v[22:23], off nt
	s_nop 0
	global_load_dword v60, v[60:61], off nt
	s_nop 0
	global_load_dword v61, v[62:63], off nt
	s_nop 0
	global_load_dword v62, v[64:65], off nt
	global_load_dword v63, v[66:67], off nt
	s_nop 0
	global_load_dword v70, v[70:71], off nt
	v_add_co_u32_e32 v16, vcc, s3, v2
	s_mov_b32 s3, 0x4d000
	s_nop 0
	v_addc_co_u32_e32 v17, vcc, 0, v3, vcc
	v_add_co_u32_e32 v18, vcc, s3, v2
	s_mov_b32 s3, 0x42000
	s_nop 0
	v_addc_co_u32_e32 v19, vcc, 0, v3, vcc
	v_add_co_u32_e32 v22, vcc, s3, v2
	s_mov_b32 s3, 0x37000
	s_nop 0
	v_addc_co_u32_e32 v23, vcc, 0, v3, vcc
	v_add_co_u32_e32 v66, vcc, s3, v2
	s_mov_b32 s3, 0x2c000
	s_nop 0
	v_addc_co_u32_e32 v67, vcc, 0, v3, vcc
	v_add_co_u32_e32 v72, vcc, s3, v2
	s_mov_b32 s3, 0x21000
	s_nop 0
	v_addc_co_u32_e32 v73, vcc, 0, v3, vcc
	v_add_co_u32_e32 v80, vcc, s3, v2
	s_mov_b32 s3, 0x16000
	s_nop 0
	v_addc_co_u32_e32 v81, vcc, 0, v3, vcc
	v_add_co_u32_e32 v82, vcc, s3, v2
	s_mov_b32 s15, 0xb000
	s_nop 0
	v_addc_co_u32_e32 v83, vcc, 0, v3, vcc
	v_add_co_u32_e32 v84, vcc, s15, v2
	s_mov_b32 s3, 0x273000
	s_nop 0
	v_addc_co_u32_e32 v85, vcc, 0, v3, vcc
	global_load_dword v79, v[16:17], off nt
	global_load_dword v71, v[18:19], off nt
	global_load_dword v64, v[22:23], off nt
	global_load_dword v65, v[66:67], off nt
	s_nop 0
	global_load_dword v66, v[72:73], off nt
	global_load_dword v67, v[80:81], off nt
	global_load_dword v68, v[82:83], off nt
	s_nop 0
	global_load_dword v72, v[84:85], off nt
	v_add_co_u32_e32 v16, vcc, s3, v2
	s_ashr_i32 s3, s2, 31
	s_nop 0
	v_addc_co_u32_e32 v17, vcc, 0, v3, vcc
	global_load_dword v85, v[4:5], off nt
	global_load_dword v21, v[6:7], off nt
	global_load_dword v80, v[8:9], off nt
	global_load_dword v81, v[10:11], off nt
	global_load_dword v82, v[12:13], off nt
	global_load_dword v83, v[14:15], off nt
	global_load_dword v84, v[16:17], off nt
	global_load_dword v73, v[2:3], off nt
	s_lshl_b64 s[2:3], s[2:3], 12
	s_add_u32 s9, s13, s2
	v_lshrrev_b32_e32 v4, 3, v1
	v_lshlrev_b32_e32 v2, 3, v0
	s_addc_u32 s16, s14, s3
	s_lshl_b64 s[2:3], s[6:7], 1
	v_and_b32_e32 v2, 56, v2
	v_lshlrev_b32_e32 v5, 2, v4
	s_add_u32 s6, s9, s2
	v_lshlrev_b32_e32 v4, 11, v4
	v_mul_u32_u24_e32 v3, 0x104, v2
	s_addc_u32 s7, s16, s3
	s_add_i32 s2, s12, s11
	v_or_b32_e32 v6, 0x4000, v4
	v_or_b32_e32 v8, 0x8000, v4
	v_or_b32_e32 v10, 0xc000, v4
	v_or_b32_e32 v12, 0x10000, v4
	v_or_b32_e32 v14, 0x14000, v4
	v_or_b32_e32 v16, 0x18000, v4
	v_or_b32_e32 v18, 0x1c000, v4
	v_add3_u32 v22, s8, v3, v5
	v_lshlrev_b32_e32 v2, 1, v2
	v_mov_b32_e32 v3, 0
	s_lshl_b32 s16, s2, 6
	s_lshl_b32 s17, s97, 9
	s_lshl_b32 s18, s2, 5
	s_lshl_b32 s19, s97, 8
	v_lshlrev_b32_e32 v4, 1, v4
	v_lshlrev_b32_e32 v6, 1, v6
	v_lshlrev_b32_e32 v8, 1, v8
	v_lshlrev_b32_e32 v10, 1, v10
	v_lshlrev_b32_e32 v12, 1, v12
	v_lshlrev_b32_e32 v14, 1, v14
	v_lshlrev_b32_e32 v16, 1, v16
	v_lshlrev_b32_e32 v18, 1, v18
	s_mov_b64 s[2:3], s[6:7]
	v_lshl_add_u32 v23, v1, 2, s8
	s_branch .LBB0_9

; __device__ __forceinline__ void tr_range(const Params& p, LAS unsigned char* lds, int first, int stride, int end, int lane, int wave) {
;     ...
;     for (int it = first; it < end; it += stride) {
; #pragma unroll
;         for (int i = 0; i < 64; ++i) scr[i * 65 + lane] = ra[i];
;         const bool more = it + stride < end;
;         TrItem nxt = cur;
;         if (more) { nxt = p0_item_of(p, it + stride, lane);
; #pragma unroll
;             for (int i = 0; i < 64; ++i) ra[i] = nxt.src[(size_t)i * nxt.N]; }
.LBB0_9:
	v_add_u32_e32 v5, 0x400, v23
	s_waitcnt vmcnt(0)
	ds_write2_b32 v23, v73, v72 offset1:65
	ds_write2_b32 v23, v68, v67 offset0:130 offset1:195
	ds_write2_b32 v5, v66, v65 offset0:4 offset1:69
	ds_write2_b32 v5, v64, v71 offset0:134 offset1:199
	v_add_u32_e32 v5, 0x800, v23
	ds_write2_b32 v5, v79, v70 offset0:8 offset1:73
	ds_write2_b32 v5, v63, v62 offset0:138 offset1:203
	v_add_u32_e32 v5, 0xc00, v23
	ds_write2_b32 v5, v61, v60 offset0:12 offset1:77
	ds_write2_b32 v5, v59, v69 offset0:142 offset1:207
	v_add_u32_e32 v5, 0x1000, v23
	ds_write2_b32 v5, v78, v58 offset0:16 offset1:81
	ds_write2_b32 v5, v48, v47 offset0:146 offset1:211
	v_add_u32_e32 v5, 0x1400, v23
	ds_write2_b32 v5, v46, v45 offset0:20 offset1:85
	ds_write2_b32 v5, v44, v57 offset0:150 offset1:215
	v_add_u32_e32 v5, 0x1800, v23
	ds_write2_b32 v5, v77, v56 offset0:24 offset1:89
	ds_write2_b32 v5, v43, v42 offset0:154 offset1:219
	v_add_u32_e32 v5, 0x1c00, v23
	ds_write2_b32 v5, v41, v40 offset0:28 offset1:93
	ds_write2_b32 v5, v39, v55 offset0:158 offset1:223
	v_add_u32_e32 v5, 0x2000, v23
	ds_write2_b32 v5, v76, v54 offset0:32 offset1:97
	ds_write2_b32 v5, v38, v37 offset0:162 offset1:227
	v_add_u32_e32 v5, 0x2400, v23
	ds_write2_b32 v5, v36, v35 offset0:36 offset1:101
	ds_write2_b32 v5, v34, v53 offset0:166 offset1:231
	v_add_u32_e32 v5, 0x2800, v23
	ds_write2_b32 v5, v75, v52 offset0:40 offset1:105
	ds_write2_b32 v5, v33, v32 offset0:170 offset1:235
	v_add_u32_e32 v5, 0x2c00, v23
	ds_write2_b32 v5, v31, v30 offset0:44 offset1:109
	ds_write2_b32 v5, v29, v51 offset0:174 offset1:239
	v_add_u32_e32 v5, 0x3000, v23
	s_add_i32 s11, s11, s12
	ds_write2_b32 v5, v74, v50 offset0:48 offset1:113
	ds_write2_b32 v5, v28, v27 offset0:178 offset1:243
	v_add_u32_e32 v5, 0x3400, v23
	s_cmpk_gt_i32 s11, 0x15ff
	ds_write2_b32 v5, v26, v25 offset0:52 offset1:117
	ds_write2_b32 v5, v24, v49 offset0:182 offset1:247
	v_add_u32_e32 v5, 0x3800, v23
	s_cselect_b64 s[8:9], -1, 0
	ds_write2_b32 v5, v20, v84 offset0:56 offset1:121
	ds_write2_b32 v5, v83, v82 offset0:186 offset1:251
	v_add_u32_e32 v5, 0x3c00, v23
	s_and_b64 vcc, exec, s[8:9]
	ds_write2_b32 v5, v81, v80 offset0:60 offset1:125
	ds_write2_b32 v5, v21, v85 offset0:190 offset1:255
	s_cbranch_vccnz .LBB0_8
	s_mul_hi_i32 s2, s11, 0x2e8ba2e9
	s_lshr_b32 s3, s2, 31
	s_ashr_i32 s2, s2, 5
	s_add_i32 s22, s2, s3
	s_mul_i32 s21, s22, 0xffffea00
	s_mul_i32 s2, s22, 0xffffd400
	s_bfe_i32 s20, s11, 0x10001
	s_add_i32 s21, s18, s21
	s_add_i32 s2, s16, s2
	s_and_b32 s20, s20, 0x1600
	s_and_b32 s21, s21, 0xffffff80
	s_and_b32 s3, s2, 64
	s_add_i32 s20, s20, s21
	s_or_b32 s3, s20, s3
	v_or_b32_e32 v20, s3, v1
	s_lshl_b32 s20, s22, 6
	s_ashr_i32 s3, s2, 31
	s_ashr_i32 s21, s20, 31
	s_lshl_b64 s[2:3], s[2:3], 12
	s_load_dwordx16 s[36:51], s[0:1], 0x0
	s_add_u32 s23, s13, s2
	s_addc_u32 s24, s14, s3
	s_lshl_b64 s[2:3], s[20:21], 1
	s_add_u32 s2, s23, s2
	s_addc_u32 s3, s24, s3
	s_mul_i32 s22, s22, 0x2c0000
	s_mul_hi_i32 s21, s20, 0xb000
	s_waitcnt lgkmcnt(0)
	s_add_u32 s20, s50, s22
	s_addc_u32 s21, s51, s21
	v_ashrrev_i32_e32 v21, 31, v20
	v_lshl_add_u64 v[20:21], v[20:21], 2, s[20:21]
	v_add_co_u32_e32 v24, vcc, s15, v20
	s_nop 1
	v_addc_co_u32_e32 v25, vcc, 0, v21, vcc
	v_add_co_u32_e32 v26, vcc, 0x16000, v20
	s_nop 1
	v_addc_co_u32_e32 v27, vcc, 0, v21, vcc
	v_add_co_u32_e32 v28, vcc, 0x21000, v20
	s_nop 1
	v_addc_co_u32_e32 v29, vcc, 0, v21, vcc
	v_add_co_u32_e32 v30, vcc, 0x2c000, v20
	s_nop 1
	v_addc_co_u32_e32 v31, vcc, 0, v21, vcc
	v_add_co_u32_e32 v32, vcc, 0x37000, v20
	s_nop 1
	v_addc_co_u32_e32 v33, vcc, 0, v21, vcc
	v_add_co_u32_e32 v34, vcc, 0x42000, v20
	s_nop 1
	v_addc_co_u32_e32 v35, vcc, 0, v21, vcc
	v_add_co_u32_e32 v36, vcc, 0x4d000, v20
	s_nop 1
	v_addc_co_u32_e32 v37, vcc, 0, v21, vcc
	global_load_dword v73, v[20:21], off nt
	global_load_dword v72, v[24:25], off nt
	global_load_dword v68, v[26:27], off nt
	global_load_dword v67, v[28:29], off nt
	global_load_dword v66, v[30:31], off nt
	global_load_dword v65, v[32:33], off nt
	global_load_dword v64, v[34:35], off nt
	global_load_dword v71, v[36:37], off nt
	v_add_co_u32_e32 v24, vcc, 0x58000, v20
	s_nop 1
	v_addc_co_u32_e32 v25, vcc, 0, v21, vcc
	v_add_co_u32_e32 v26, vcc, 0x63000, v20
	s_nop 1
	v_addc_co_u32_e32 v27, vcc, 0, v21, vcc
	v_add_co_u32_e32 v28, vcc, 0x6e000, v20
	s_nop 1
	v_addc_co_u32_e32 v29, vcc, 0, v21, vcc
	v_add_co_u32_e32 v30, vcc, 0x79000, v20
	s_nop 1
	v_addc_co_u32_e32 v31, vcc, 0, v21, vcc
	v_add_co_u32_e32 v32, vcc, 0x84000, v20
	s_nop 1
	v_addc_co_u32_e32 v33, vcc, 0, v21, vcc
	v_add_co_u32_e32 v34, vcc, 0x8f000, v20
	s_nop 1
	v_addc_co_u32_e32 v35, vcc, 0, v21, vcc
	v_add_co_u32_e32 v36, vcc, 0x9a000, v20
	s_nop 1
	v_addc_co_u32_e32 v37, vcc, 0, v21, vcc
	v_add_co_u32_e32 v38, vcc, 0xa5000, v20
	s_nop 1
	v_addc_co_u32_e32 v39, vcc, 0, v21, vcc
	global_load_dword v79, v[24:25], off nt
	global_load_dword v70, v[26:27], off nt
	global_load_dword v63, v[28:29], off nt
	global_load_dword v62, v[30:31], off nt
	global_load_dword v61, v[32:33], off nt
	global_load_dword v60, v[34:35], off nt
	global_load_dword v59, v[36:37], off nt
	global_load_dword v69, v[38:39], off nt
	v_add_co_u32_e32 v24, vcc, 0xb0000, v20
	s_nop 1
	v_addc_co_u32_e32 v25, vcc, 0, v21, vcc
	v_add_co_u32_e32 v26, vcc, 0xbb000, v20
	s_nop 1
	v_addc_co_u32_e32 v27, vcc, 0, v21, vcc
	v_add_co_u32_e32 v28, vcc, 0xc6000, v20
	s_nop 1
	v_addc_co_u32_e32 v29, vcc, 0, v21, vcc
	v_add_co_u32_e32 v30, vcc, 0xd1000, v20
	s_nop 1
	v_addc_co_u32_e32 v31, vcc, 0, v21, vcc
	v_add_co_u32_e32 v32, vcc, 0xdc000, v20
	s_nop 1
	v_addc_co_u32_e32 v33, vcc, 0, v21, vcc
	v_add_co_u32_e32 v34, vcc, 0xe7000, v20
; __device__ __forceinline__ void tr_range(const Params& p, LAS unsigned char* lds, int first, int stride, int end, int lane, int wave) {
;     ...
;         if (more) { nxt = p0_item_of(p, it + stride, lane);
; #pragma unroll
;             for (int i = 0; i < 64; ++i) ra[i] = nxt.src[(size_t)i * nxt.N]; }
	s_nop 1
	v_addc_co_u32_e32 v35, vcc, 0, v21, vcc
	v_add_co_u32_e32 v36, vcc, 0xf2000, v20
	s_nop 1
	v_addc_co_u32_e32 v37, vcc, 0, v21, vcc
	v_add_co_u32_e32 v38, vcc, 0xfd000, v20
	s_nop 1
	v_addc_co_u32_e32 v39, vcc, 0, v21, vcc
	global_load_dword v78, v[24:25], off nt
	global_load_dword v58, v[26:27], off nt
	global_load_dword v48, v[28:29], off nt
	global_load_dword v47, v[30:31], off nt
	global_load_dword v46, v[32:33], off nt
	global_load_dword v45, v[34:35], off nt
	global_load_dword v44, v[36:37], off nt
	global_load_dword v57, v[38:39], off nt
	v_add_co_u32_e32 v24, vcc, 0x108000, v20
	s_nop 1
	v_addc_co_u32_e32 v25, vcc, 0, v21, vcc
	v_add_co_u32_e32 v26, vcc, 0x113000, v20
	s_nop 1
	v_addc_co_u32_e32 v27, vcc, 0, v21, vcc
	v_add_co_u32_e32 v28, vcc, 0x11e000, v20
	s_nop 1
	v_addc_co_u32_e32 v29, vcc, 0, v21, vcc
	v_add_co_u32_e32 v30, vcc, 0x129000, v20
	s_nop 1
	v_addc_co_u32_e32 v31, vcc, 0, v21, vcc
	v_add_co_u32_e32 v32, vcc, 0x134000, v20
	s_nop 1
	v_addc_co_u32_e32 v33, vcc, 0, v21, vcc
	v_add_co_u32_e32 v34, vcc, 0x13f000, v20
	s_nop 1
	v_addc_co_u32_e32 v35, vcc, 0, v21, vcc
	v_add_co_u32_e32 v36, vcc, 0x14a000, v20
	s_nop 1
	v_addc_co_u32_e32 v37, vcc, 0, v21, vcc
	v_add_co_u32_e32 v50, vcc, 0x155000, v20
	s_nop 1
	v_addc_co_u32_e32 v51, vcc, 0, v21, vcc
	global_load_dword v77, v[24:25], off nt
	global_load_dword v56, v[26:27], off nt
	global_load_dword v43, v[28:29], off nt
	global_load_dword v42, v[30:31], off nt
	global_load_dword v41, v[32:33], off nt
	global_load_dword v40, v[34:35], off nt
	global_load_dword v39, v[36:37], off nt
	global_load_dword v55, v[50:51], off nt
	v_add_co_u32_e32 v24, vcc, 0x160000, v20
	s_nop 1
	v_addc_co_u32_e32 v25, vcc, 0, v21, vcc
	v_add_co_u32_e32 v26, vcc, 0x16b000, v20
	s_nop 1
	v_addc_co_u32_e32 v27, vcc, 0, v21, vcc
	v_add_co_u32_e32 v28, vcc, 0x176000, v20
	s_nop 1
	v_addc_co_u32_e32 v29, vcc, 0, v21, vcc
	v_add_co_u32_e32 v30, vcc, 0x181000, v20
	s_nop 1
	v_addc_co_u32_e32 v31, vcc, 0, v21, vcc
	v_add_co_u32_e32 v32, vcc, 0x18c000, v20
	s_nop 1
	v_addc_co_u32_e32 v33, vcc, 0, v21, vcc
	v_add_co_u32_e32 v34, vcc, 0x197000, v20
	s_nop 1
	v_addc_co_u32_e32 v35, vcc, 0, v21, vcc
	v_add_co_u32_e32 v50, vcc, 0x1a2000, v20
	s_nop 1
	v_addc_co_u32_e32 v51, vcc, 0, v21, vcc
	v_add_co_u32_e32 v52, vcc, 0x1ad000, v20
	s_nop 1
	v_addc_co_u32_e32 v53, vcc, 0, v21, vcc
	global_load_dword v76, v[24:25], off nt
	global_load_dword v54, v[26:27], off nt
	global_load_dword v38, v[28:29], off nt
	global_load_dword v37, v[30:31], off nt
	global_load_dword v36, v[32:33], off nt
	s_nop 0
	global_load_dword v35, v[34:35], off nt
	s_nop 0
	global_load_dword v34, v[50:51], off nt
	s_nop 0
	global_load_dword v53, v[52:53], off nt
	v_add_co_u32_e32 v24, vcc, 0x1b8000, v20
	s_nop 1
	v_addc_co_u32_e32 v25, vcc, 0, v21, vcc
	v_add_co_u32_e32 v26, vcc, 0x1c3000, v20
	s_nop 1
	v_addc_co_u32_e32 v27, vcc, 0, v21, vcc
	v_add_co_u32_e32 v28, vcc, 0x1ce000, v20
	s_nop 1
	v_addc_co_u32_e32 v29, vcc, 0, v21, vcc
	v_add_co_u32_e32 v30, vcc, 0x1d9000, v20
	s_nop 1
	v_addc_co_u32_e32 v31, vcc, 0, v21, vcc
	v_add_co_u32_e32 v50, vcc, 0x1e4000, v20
	s_nop 1
	v_addc_co_u32_e32 v51, vcc, 0, v21, vcc
	v_add_co_u32_e32 v80, vcc, 0x1ef000, v20
	s_nop 1
	v_addc_co_u32_e32 v81, vcc, 0, v21, vcc
	v_add_co_u32_e32 v82, vcc, 0x1fa000, v20
	s_nop 1
	v_addc_co_u32_e32 v83, vcc, 0, v21, vcc
	v_add_co_u32_e32 v84, vcc, 0x205000, v20
	s_nop 1
	v_addc_co_u32_e32 v85, vcc, 0, v21, vcc
	global_load_dword v75, v[24:25], off nt
	global_load_dword v52, v[26:27], off nt
	global_load_dword v33, v[28:29], off nt
	global_load_dword v32, v[30:31], off nt
	s_nop 0
	global_load_dword v31, v[50:51], off nt
	global_load_dword v30, v[80:81], off nt
	global_load_dword v29, v[82:83], off nt
	s_nop 0
	global_load_dword v51, v[84:85], off nt
	v_add_co_u32_e32 v24, vcc, 0x210000, v20
	s_nop 1
	v_addc_co_u32_e32 v25, vcc, 0, v21, vcc
	v_add_co_u32_e32 v26, vcc, 0x21b000, v20
	s_nop 1
	v_addc_co_u32_e32 v27, vcc, 0, v21, vcc
	v_add_co_u32_e32 v80, vcc, 0x226000, v20
	s_nop 1
	v_addc_co_u32_e32 v81, vcc, 0, v21, vcc
	v_add_co_u32_e32 v82, vcc, 0x231000, v20
	s_nop 1
	v_addc_co_u32_e32 v83, vcc, 0, v21, vcc
	v_add_co_u32_e32 v84, vcc, 0x23c000, v20
	s_nop 1
	v_addc_co_u32_e32 v85, vcc, 0, v21, vcc
	v_add_co_u32_e32 v86, vcc, 0x247000, v20
	s_nop 1
	v_addc_co_u32_e32 v87, vcc, 0, v21, vcc
	v_add_co_u32_e32 v88, vcc, 0x252000, v20
	s_nop 1
	v_addc_co_u32_e32 v89, vcc, 0, v21, vcc
	v_add_co_u32_e32 v90, vcc, 0x25d000, v20
	s_nop 1
	v_addc_co_u32_e32 v91, vcc, 0, v21, vcc
	global_load_dword v74, v[24:25], off nt
	global_load_dword v50, v[26:27], off nt
	global_load_dword v28, v[80:81], off nt
	s_nop 0
	global_load_dword v27, v[82:83], off nt
	global_load_dword v26, v[84:85], off nt
	global_load_dword v25, v[86:87], off nt
	global_load_dword v24, v[88:89], off nt
	global_load_dword v49, v[90:91], off nt
	v_add_co_u32_e32 v80, vcc, 0x268000, v20
	s_nop 1
	v_addc_co_u32_e32 v81, vcc, 0, v21, vcc
	v_add_co_u32_e32 v82, vcc, 0x273000, v20
	s_nop 1
	v_addc_co_u32_e32 v83, vcc, 0, v21, vcc
	v_add_co_u32_e32 v86, vcc, 0x27e000, v20
	s_nop 1
	v_addc_co_u32_e32 v87, vcc, 0, v21, vcc
	v_add_co_u32_e32 v88, vcc, 0x289000, v20
	s_nop 1
	v_addc_co_u32_e32 v89, vcc, 0, v21, vcc
	v_add_co_u32_e32 v90, vcc, 0x294000, v20
	s_nop 1
	v_addc_co_u32_e32 v91, vcc, 0, v21, vcc
	v_add_co_u32_e32 v92, vcc, 0x29f000, v20
	s_nop 1
	v_addc_co_u32_e32 v93, vcc, 0, v21, vcc
	v_add_co_u32_e32 v94, vcc, 0x2aa000, v20
	s_nop 1
	v_addc_co_u32_e32 v95, vcc, 0, v21, vcc
	v_add_co_u32_e32 v96, vcc, 0x2b5000, v20
	s_nop 1
	v_addc_co_u32_e32 v97, vcc, 0, v21, vcc
	global_load_dword v20, v[80:81], off nt
	global_load_dword v84, v[82:83], off nt
	s_nop 0
	global_load_dword v83, v[86:87], off nt
	global_load_dword v82, v[88:89], off nt
	global_load_dword v81, v[90:91], off nt
	global_load_dword v80, v[92:93], off nt
	global_load_dword v21, v[94:95], off nt
	global_load_dword v85, v[96:97], off nt
	s_branch .LBB0_8

; #define LAS __attribute__((address_space(3)))
; __device__ __forceinline__ TrItem p0_item_of(const Params& p, int it, int lane) {
;     ...
;     const int nblk = N / 64, kb = r / nblk, nb = r % nblk, k0 = 64 * kb, n0 = 64 * nb;
;     TrItem t; t.src = W + (size_t)k0 * N + srccol(map, n0 + lane); t.N = N; t.K = K; t.fp8 = f8;
;     t.dst = f8 ? (bf16*)((unsigned char*)WT + (size_t)n0 * K + k0) : WT + (size_t)n0 * K + k0; return t;
; }
; __device__ __forceinline__ void tr_range(const Params& p, LAS unsigned char* lds, int first, int stride, int end, int lane, int wave) {
;     LAS float* scr = (LAS float*)(lds + wave * (64 * 65 * 4));
;     if (first >= end) return;
;     float ra[64];
;     TrItem cur = p0_item_of(p, first, lane);
; #pragma unroll
;     for (int i = 0; i < 64; ++i) ra[i] = cur.src[(size_t)i * cur.N];
.LBB0_263:
	s_add_u32 s16, s88, s6
	s_addc_u32 s7, s89, s7
	s_lshl_b32 s10, s14, 6
	s_ashr_i32 s11, s10, 31
	v_readlane_b32 s23, v253, 31
	s_mul_i32 s14, s11, s0
	s_mul_hi_u32 s15, s10, s0
	s_sub_i32 s1, s97, s12
	s_mul_i32 s6, s23, 0x4100
	s_add_i32 s15, s15, s14
	s_mul_i32 s14, s10, s0
	s_lshl_b32 s20, s1, 3
	s_add_i32 s6, s6, 0
	s_lshl_b64 s[14:15], s[14:15], 2
	s_add_u32 s2, s2, s14
	s_addc_u32 s3, s3, s15
	v_ashrrev_i32_e32 v3, 31, v2
	v_lshl_add_u64 v[2:3], v[2:3], 2, s[2:3]
	s_mul_hi_i32 s3, s13, s19
	s_mul_i32 s2, s13, s19
	s_lshl_b64 s[14:15], s[2:3], 1
	s_add_u32 s13, s16, s14
	s_addc_u32 s17, s7, s15
	s_lshl_b64 s[14:15], s[10:11], 1
	s_add_u32 s13, s13, s14
	s_addc_u32 s14, s17, s15
	s_add_u32 s2, s16, s2
	s_addc_u32 s3, s7, s3
	s_add_u32 s7, s2, s10
	s_mov_b32 s1, 0
	s_addc_u32 s10, s3, s11
	s_and_b64 s[2:3], s[8:9], exec
	s_mul_i32 s8, s0, 63
	s_mov_b32 s9, s1
	v_lshl_add_u64 v[4:5], s[8:9], 2, v[2:3]
	s_mul_i32 s8, s0, 62
	s_waitcnt vmcnt(0)
	v_lshl_add_u64 v[6:7], s[8:9], 2, v[2:3]
	s_mul_i32 s8, s0, 61
	v_lshl_add_u64 v[8:9], s[8:9], 2, v[2:3]
	s_mul_i32 s8, s0, 60
	v_lshl_add_u64 v[10:11], s[8:9], 2, v[2:3]
	s_mul_i32 s8, s0, 59
	v_lshl_add_u64 v[12:13], s[8:9], 2, v[2:3]
	s_mul_i32 s8, s0, 58
	v_lshl_add_u64 v[14:15], s[8:9], 2, v[2:3]
	s_mul_i32 s8, s0, 57
	v_lshl_add_u64 v[16:17], s[8:9], 2, v[2:3]
	s_mul_i32 s8, s0, 56
	v_lshl_add_u64 v[18:19], s[8:9], 2, v[2:3]
	s_mul_i32 s8, s0, 55
	v_lshl_add_u64 v[20:21], s[8:9], 2, v[2:3]
	s_mul_i32 s8, s0, 54
	v_lshl_add_u64 v[22:23], s[8:9], 2, v[2:3]
	s_mul_i32 s8, s0, 53
	v_lshl_add_u64 v[24:25], s[8:9], 2, v[2:3]
	s_mul_i32 s8, s0, 52
	v_lshl_add_u64 v[26:27], s[8:9], 2, v[2:3]
	s_mul_i32 s8, s0, 51
	v_lshl_add_u64 v[30:31], s[8:9], 2, v[2:3]
	s_mul_i32 s8, s0, 50
	v_lshl_add_u64 v[38:39], s[8:9], 2, v[2:3]
	s_mul_i32 s8, s0, 49
	v_lshl_add_u64 v[40:41], s[8:9], 2, v[2:3]
	s_mul_i32 s8, s0, 48
	global_load_dword v28, v[18:19], off nt
	global_load_dword v32, v[20:21], off nt
	global_load_dword v33, v[22:23], off nt
	global_load_dword v34, v[24:25], off nt
	global_load_dword v35, v[26:27], off nt
	global_load_dword v36, v[30:31], off nt
	global_load_dword v37, v[38:39], off nt
	s_nop 0
	global_load_dword v38, v[40:41], off nt
	v_lshl_add_u64 v[18:19], s[8:9], 2, v[2:3]
	s_mul_i32 s8, s0, 47
	v_lshl_add_u64 v[20:21], s[8:9], 2, v[2:3]
	s_mul_i32 s8, s0, 46
	v_lshl_add_u64 v[22:23], s[8:9], 2, v[2:3]
	s_mul_i32 s8, s0, 45
	v_lshl_add_u64 v[24:25], s[8:9], 2, v[2:3]
	s_mul_i32 s8, s0, 44
	v_lshl_add_u64 v[26:27], s[8:9], 2, v[2:3]
	s_mul_i32 s8, s0, 43
	v_lshl_add_u64 v[30:31], s[8:9], 2, v[2:3]
	s_mul_i32 s8, s0, 42
	v_lshl_add_u64 v[44:45], s[8:9], 2, v[2:3]
	s_mul_i32 s8, s0, 41
	v_lshl_add_u64 v[46:47], s[8:9], 2, v[2:3]
	s_mul_i32 s8, s0, 40
	global_load_dword v75, v[18:19], off nt
	global_load_dword v39, v[20:21], off nt
	global_load_dword v40, v[22:23], off nt
	global_load_dword v41, v[24:25], off nt
	global_load_dword v42, v[26:27], off nt
	global_load_dword v43, v[30:31], off nt
	s_nop 0
	global_load_dword v44, v[44:45], off nt
	s_nop 0
	global_load_dword v45, v[46:47], off nt
	v_lshl_add_u64 v[18:19], s[8:9], 2, v[2:3]
	s_mul_i32 s8, s0, 39
	v_lshl_add_u64 v[20:21], s[8:9], 2, v[2:3]
	s_mul_i32 s8, s0, 38
	v_lshl_add_u64 v[22:23], s[8:9], 2, v[2:3]
	s_mul_i32 s8, s0, 37
	v_lshl_add_u64 v[24:25], s[8:9], 2, v[2:3]
	s_mul_i32 s8, s0, 36
	v_lshl_add_u64 v[26:27], s[8:9], 2, v[2:3]
	s_mul_i32 s8, s0, 35
	v_lshl_add_u64 v[30:31], s[8:9], 2, v[2:3]
	s_mul_i32 s8, s0, 34
	v_lshl_add_u64 v[52:53], s[8:9], 2, v[2:3]
	s_mul_i32 s8, s0, 33
	s_cselect_b32 s3, s14, s10
	s_cselect_b32 s2, s13, s7
	v_lshl_add_u64 v[54:55], s[8:9], 2, v[2:3]
	s_lshl_b32 s8, s0, 5
	global_load_dword v76, v[18:19], off nt
	global_load_dword v46, v[20:21], off nt
	global_load_dword v47, v[22:23], off nt
	global_load_dword v48, v[24:25], off nt
	global_load_dword v49, v[26:27], off nt
	global_load_dword v50, v[30:31], off nt
	global_load_dword v51, v[52:53], off nt
	s_nop 0
	global_load_dword v52, v[54:55], off nt
	v_lshl_add_u64 v[18:19], s[8:9], 2, v[2:3]
	s_mul_i32 s8, s0, 31
	v_lshl_add_u64 v[20:21], s[8:9], 2, v[2:3]
	s_mul_i32 s8, s0, 30
	v_lshl_add_u64 v[22:23], s[8:9], 2, v[2:3]
	s_mul_i32 s8, s0, 29
	v_lshl_add_u64 v[24:25], s[8:9], 2, v[2:3]
	s_mul_i32 s8, s0, 28
	v_lshl_add_u64 v[26:27], s[8:9], 2, v[2:3]
	s_mul_i32 s8, s0, 27
	v_lshl_add_u64 v[30:31], s[8:9], 2, v[2:3]
	s_mul_i32 s8, s0, 26
	v_lshl_add_u64 v[58:59], s[8:9], 2, v[2:3]
	s_mul_i32 s8, s0, 25
	v_lshl_add_u64 v[60:61], s[8:9], 2, v[2:3]
	s_mul_i32 s8, s0, 24
	global_load_dword v77, v[18:19], off nt
	global_load_dword v53, v[20:21], off nt
	global_load_dword v54, v[22:23], off nt
; #define LAS __attribute__((address_space(3)))
; #define LDS_WAIT() asm volatile("s_waitcnt lgkmcnt(0)" ::: "memory")
; __device__ __forceinline__ void tr_range(const Params& p, LAS unsigned char* lds, int first, int stride, int end, int lane, int wave) {
;     LAS float* scr = (LAS float*)(lds + wave * (64 * 65 * 4));
;     if (first >= end) return;
;     float ra[64];
;     TrItem cur = p0_item_of(p, first, lane);
; #pragma unroll
;     for (int i = 0; i < 64; ++i) ra[i] = cur.src[(size_t)i * cur.N];
; #pragma unroll 1
;     for (int it = first; it < end; it += stride) {
; #pragma unroll
;         for (int i = 0; i < 64; ++i) scr[i * 65 + lane] = ra[i];
;         const bool more = it + stride < end;
;         TrItem nxt = cur;
;         if (more) { nxt = p0_item_of(p, it + stride, lane);
; #pragma unroll
;             for (int i = 0; i < 64; ++i) ra[i] = nxt.src[(size_t)i * nxt.N]; }
;         LDS_WAIT(); asm volatile("" ::: "memory");
;         if (cur.fp8) {
;             const int c = lane & 3;
; #pragma unroll
	global_load_dword v55, v[24:25], off nt
	global_load_dword v56, v[26:27], off nt
	global_load_dword v57, v[30:31], off nt
	s_nop 0
	global_load_dword v58, v[58:59], off nt
	s_nop 0
	global_load_dword v59, v[60:61], off nt
	v_lshl_add_u64 v[18:19], s[8:9], 2, v[2:3]
	s_mul_i32 s8, s0, 23
	v_lshl_add_u64 v[20:21], s[8:9], 2, v[2:3]
	s_mul_i32 s8, s0, 22
	v_lshl_add_u64 v[22:23], s[8:9], 2, v[2:3]
	s_mul_i32 s8, s0, 21
	v_lshl_add_u64 v[24:25], s[8:9], 2, v[2:3]
	s_mul_i32 s8, s0, 20
	v_lshl_add_u64 v[26:27], s[8:9], 2, v[2:3]
	s_mul_i32 s8, s0, 19
	v_lshl_add_u64 v[30:31], s[8:9], 2, v[2:3]
	s_mul_i32 s8, s0, 18
	v_lshl_add_u64 v[66:67], s[8:9], 2, v[2:3]
	s_mul_i32 s8, s0, 17
	v_lshl_add_u64 v[68:69], s[8:9], 2, v[2:3]
	s_lshl_b32 s8, s0, 4
	global_load_dword v78, v[18:19], off nt
	global_load_dword v60, v[20:21], off nt
	global_load_dword v61, v[22:23], off nt
	global_load_dword v62, v[24:25], off nt
	global_load_dword v63, v[26:27], off nt
	global_load_dword v64, v[30:31], off nt
	global_load_dword v65, v[66:67], off nt
	s_nop 0
	global_load_dword v66, v[68:69], off nt
	v_lshl_add_u64 v[18:19], s[8:9], 2, v[2:3]
	s_mul_i32 s8, s0, 15
	v_lshl_add_u64 v[20:21], s[8:9], 2, v[2:3]
	s_mul_i32 s8, s0, 14
	v_lshl_add_u64 v[22:23], s[8:9], 2, v[2:3]
	s_mul_i32 s8, s0, 13
	v_lshl_add_u64 v[24:25], s[8:9], 2, v[2:3]
	s_mul_i32 s8, s0, 12
	v_lshl_add_u64 v[26:27], s[8:9], 2, v[2:3]
	s_mul_i32 s8, s0, 11
	v_lshl_add_u64 v[30:31], s[8:9], 2, v[2:3]
	s_mul_i32 s8, s0, 10
	v_lshl_add_u64 v[72:73], s[8:9], 2, v[2:3]
	s_mul_i32 s8, s0, 9
	v_lshl_add_u64 v[80:81], s[8:9], 2, v[2:3]
	s_lshl_b32 s8, s0, 3
	global_load_dword v79, v[18:19], off nt
	global_load_dword v67, v[20:21], off nt
	global_load_dword v68, v[22:23], off nt
	global_load_dword v69, v[24:25], off nt
	global_load_dword v70, v[26:27], off nt
	global_load_dword v71, v[30:31], off nt
	s_nop 0
	global_load_dword v72, v[72:73], off nt
	s_nop 0
	global_load_dword v73, v[80:81], off nt
	v_lshl_add_u64 v[18:19], s[8:9], 2, v[2:3]
	s_mul_i32 s8, s0, 7
	v_lshl_add_u64 v[20:21], s[8:9], 2, v[2:3]
	s_mul_i32 s8, s0, 6
	v_lshl_add_u64 v[22:23], s[8:9], 2, v[2:3]
	s_mul_i32 s8, s0, 5
	v_lshl_add_u64 v[24:25], s[8:9], 2, v[2:3]
	s_lshl_b32 s8, s0, 2
	v_lshl_add_u64 v[26:27], s[8:9], 2, v[2:3]
	s_mul_i32 s8, s0, 3
	v_lshl_add_u64 v[30:31], s[8:9], 2, v[2:3]
	s_lshl_b32 s8, s0, 1
	v_lshl_add_u64 v[80:81], s[8:9], 2, v[2:3]
	v_lshl_add_u64 v[82:83], s[0:1], 2, v[2:3]
	global_load_dword v74, v[18:19], off nt
	s_nop 0
	global_load_dword v19, v[20:21], off nt
	s_nop 0
	global_load_dword v21, v[22:23], off nt
	s_nop 0
	global_load_dword v23, v[24:25], off nt
	s_nop 0
	global_load_dword v25, v[26:27], off nt
	s_nop 0
	global_load_dword v27, v[30:31], off nt
	s_nop 0
	global_load_dword v30, v[80:81], off nt
	global_load_dword v31, v[82:83], off nt
	global_load_dword v29, v[4:5], off nt
	s_nop 0
	global_load_dword v80, v[6:7], off nt
	global_load_dword v81, v[8:9], off nt
	global_load_dword v82, v[10:11], off nt
	global_load_dword v83, v[12:13], off nt
	global_load_dword v84, v[14:15], off nt
	s_nop 0
	global_load_dword v17, v[16:17], off nt
	s_nop 0
	global_load_dword v15, v[2:3], off nt
	v_lshlrev_b32_e32 v4, 3, v0
	v_lshrrev_b32_e32 v6, 3, v1
	v_and_b32_e32 v4, 56, v4
	v_readlane_b32 s36, v253, 10
	v_mul_u32_u24_e32 v8, 0x104, v130
	v_mul_u32_u24_e32 v11, 0x104, v4
	v_and_b32_e32 v9, 60, v1
	v_lshlrev_b32_e32 v13, 2, v6
	v_readlane_b32 s50, v253, 24
	v_lshl_add_u32 v3, v1, 2, s6
	v_add3_u32 v9, s6, v8, v9
	v_add3_u32 v11, s6, v11, v13
	v_readlane_b32 s51, v253, 25
	s_add_u32 s6, s50, 0x5800000
	s_addc_u32 s7, s51, 0
	s_lshl_b32 s0, s97, 3
	s_lshl_b32 s8, s12, 4
	s_sub_i32 s22, s0, s8
	s_lshl_b32 s0, s86, 3
	v_lshrrev_b32_e32 v2, 2, v1
	v_mov_b32_e32 v5, 0
	s_add_i32 s23, s23, s0
	s_lshl_b32 s0, s12, 3
	v_and_b32_e32 v7, 31, v0
	v_mov_b32_e32 v131, v5
	v_or_b32_e32 v8, 16, v2
	v_or_b32_e32 v10, 32, v2
	v_or_b32_e32 v12, 48, v2
	v_or_b32_e32 v14, 8, v6
	v_or_b32_e32 v16, 16, v6
	v_or_b32_e32 v18, 24, v6
	v_or_b32_e32 v20, 32, v6
	v_or_b32_e32 v22, 40, v6
	v_or_b32_e32 v24, 48, v6
	v_or_b32_e32 v26, 56, v6
	s_sub_i32 s24, 0x1600, s0
	s_mov_b32 s25, 0xc3e00000
	v_lshlrev_b32_e32 v4, 1, v4
	v_mov_b32_e32 v13, 0x43e00000
	s_mov_b32 s16, s21
	s_mov_b64 s[8:9], s[2:3]
	s_mov_b32 s17, s19
	v_readlane_b32 s37, v253, 11
	v_readlane_b32 s38, v253, 12
	v_readlane_b32 s39, v253, 13
	v_readlane_b32 s40, v253, 14
	v_readlane_b32 s41, v253, 15
	v_readlane_b32 s42, v253, 16
	v_readlane_b32 s43, v253, 17
	v_readlane_b32 s44, v253, 18
	v_readlane_b32 s45, v253, 19
	v_readlane_b32 s46, v253, 20
	v_readlane_b32 s47, v253, 21
	v_readlane_b32 s48, v253, 22
	v_readlane_b32 s49, v253, 23
	s_branch .LBB0_266

; __device__ __forceinline__ void tr_range(const Params& p, LAS unsigned char* lds, int first, int stride, int end, int lane, int wave) {
;     ...
;         const bool more = it + stride < end;
;         TrItem nxt = cur;
;         if (more) { nxt = p0_item_of(p, it + stride, lane);
; #pragma unroll
;             for (int i = 0; i < 64; ++i) ra[i] = nxt.src[(size_t)i * nxt.N]; }
.LBB0_294:
	s_add_u32 s14, s88, s10
	s_addc_u32 s15, s89, s11
	s_lshl_b32 s10, s28, 6
	s_ashr_i32 s11, s10, 31
	s_mul_hi_i32 s26, s27, s17
	s_mul_i32 s27, s27, s17
	s_add_u32 s14, s14, s27
	s_addc_u32 s15, s15, s26
	s_add_u32 s28, s14, s27
	s_addc_u32 s29, s15, s26
	s_lshl_b64 s[26:27], s[10:11], 1
	s_add_u32 s26, s28, s26
	s_addc_u32 s27, s29, s27
	s_mul_i32 s28, s11, s0
	s_mul_hi_u32 s29, s10, s0
	s_add_i32 s29, s29, s28
	s_mul_i32 s28, s10, s0
	s_lshl_b64 s[28:29], s[28:29], 2
	s_add_u32 s12, s12, s28
	s_addc_u32 s13, s13, s29
	v_ashrrev_i32_e32 v29, 31, v28
	v_lshl_add_u64 v[28:29], v[28:29], 2, s[12:13]
	s_lshl_b32 s12, s0, 1
	s_mov_b32 s13, s1
	v_lshl_add_u64 v[32:33], s[12:13], 2, v[28:29]
	s_mul_i32 s12, s0, 3
	v_lshl_add_u64 v[34:35], s[12:13], 2, v[28:29]
	s_lshl_b32 s12, s0, 2
	v_lshl_add_u64 v[36:37], s[12:13], 2, v[28:29]
	s_mul_i32 s12, s0, 5
	v_lshl_add_u64 v[38:39], s[12:13], 2, v[28:29]
	s_mul_i32 s12, s0, 6
	v_lshl_add_u64 v[40:41], s[12:13], 2, v[28:29]
	s_mul_i32 s12, s0, 7
	v_lshl_add_u64 v[30:31], s[0:1], 2, v[28:29]
	v_lshl_add_u64 v[42:43], s[12:13], 2, v[28:29]
	s_lshl_b32 s12, s0, 3
	global_load_dword v15, v[28:29], off nt
	s_nop 0
	global_load_dword v31, v[30:31], off nt
	s_nop 0
	global_load_dword v30, v[32:33], off nt
	global_load_dword v27, v[34:35], off nt
	global_load_dword v25, v[36:37], off nt
	global_load_dword v23, v[38:39], off nt
	global_load_dword v21, v[40:41], off nt
	global_load_dword v19, v[42:43], off nt
	v_lshl_add_u64 v[32:33], s[12:13], 2, v[28:29]
	s_mul_i32 s12, s0, 9
	v_lshl_add_u64 v[34:35], s[12:13], 2, v[28:29]
	s_mul_i32 s12, s0, 10
	v_lshl_add_u64 v[36:37], s[12:13], 2, v[28:29]
	s_mul_i32 s12, s0, 11
	v_lshl_add_u64 v[38:39], s[12:13], 2, v[28:29]
	s_mul_i32 s12, s0, 12
	v_lshl_add_u64 v[40:41], s[12:13], 2, v[28:29]
	s_mul_i32 s12, s0, 13
	v_lshl_add_u64 v[42:43], s[12:13], 2, v[28:29]
	s_mul_i32 s12, s0, 14
	v_lshl_add_u64 v[44:45], s[12:13], 2, v[28:29]
	s_mul_i32 s12, s0, 15
	v_lshl_add_u64 v[46:47], s[12:13], 2, v[28:29]
	s_lshl_b32 s12, s0, 4
	global_load_dword v74, v[32:33], off nt
	global_load_dword v73, v[34:35], off nt
	global_load_dword v72, v[36:37], off nt
	global_load_dword v71, v[38:39], off nt
	global_load_dword v70, v[40:41], off nt
	global_load_dword v69, v[42:43], off nt
	global_load_dword v68, v[44:45], off nt
	global_load_dword v67, v[46:47], off nt
	v_lshl_add_u64 v[32:33], s[12:13], 2, v[28:29]
	s_mul_i32 s12, s0, 17
	v_lshl_add_u64 v[34:35], s[12:13], 2, v[28:29]
	s_mul_i32 s12, s0, 18
	v_lshl_add_u64 v[36:37], s[12:13], 2, v[28:29]
	s_mul_i32 s12, s0, 19
	v_lshl_add_u64 v[38:39], s[12:13], 2, v[28:29]
	s_mul_i32 s12, s0, 20
	v_lshl_add_u64 v[40:41], s[12:13], 2, v[28:29]
	s_mul_i32 s12, s0, 21
	v_lshl_add_u64 v[42:43], s[12:13], 2, v[28:29]
	s_mul_i32 s12, s0, 22
	v_lshl_add_u64 v[44:45], s[12:13], 2, v[28:29]
	s_mul_i32 s12, s0, 23
	v_lshl_add_u64 v[46:47], s[12:13], 2, v[28:29]
	s_mul_i32 s12, s0, 24
	global_load_dword v79, v[32:33], off nt
	global_load_dword v66, v[34:35], off nt
	global_load_dword v65, v[36:37], off nt
	global_load_dword v64, v[38:39], off nt
	global_load_dword v63, v[40:41], off nt
	global_load_dword v62, v[42:43], off nt
	global_load_dword v61, v[44:45], off nt
	global_load_dword v60, v[46:47], off nt
	v_lshl_add_u64 v[32:33], s[12:13], 2, v[28:29]
	s_mul_i32 s12, s0, 25
	v_lshl_add_u64 v[34:35], s[12:13], 2, v[28:29]
	s_mul_i32 s12, s0, 26
	v_lshl_add_u64 v[36:37], s[12:13], 2, v[28:29]
	s_mul_i32 s12, s0, 27
	v_lshl_add_u64 v[38:39], s[12:13], 2, v[28:29]
	s_mul_i32 s12, s0, 28
	v_lshl_add_u64 v[40:41], s[12:13], 2, v[28:29]
	s_mul_i32 s12, s0, 29
	v_lshl_add_u64 v[42:43], s[12:13], 2, v[28:29]
	s_mul_i32 s12, s0, 30
	v_lshl_add_u64 v[44:45], s[12:13], 2, v[28:29]
	s_mul_i32 s12, s0, 31
	v_lshl_add_u64 v[46:47], s[12:13], 2, v[28:29]
	s_lshl_b32 s12, s0, 5
	global_load_dword v78, v[32:33], off nt
	global_load_dword v59, v[34:35], off nt
	global_load_dword v58, v[36:37], off nt
; __device__ __forceinline__ TrItem p0_item_of(const Params& p, int it, int lane) {
;     ...
;     t.dst = f8 ? (bf16*)((unsigned char*)WT + (size_t)n0 * K + k0) : WT + (size_t)n0 * K + k0; return t;
; __device__ __forceinline__ void tr_range(const Params& p, LAS unsigned char* lds, int first, int stride, int end, int lane, int wave) {
;     ...
;         if (more) { nxt = p0_item_of(p, it + stride, lane);
; #pragma unroll
;             for (int i = 0; i < 64; ++i) ra[i] = nxt.src[(size_t)i * nxt.N]; }
	global_load_dword v57, v[38:39], off nt
	global_load_dword v56, v[40:41], off nt
	global_load_dword v55, v[42:43], off nt
	global_load_dword v54, v[44:45], off nt
	global_load_dword v53, v[46:47], off nt
	v_lshl_add_u64 v[32:33], s[12:13], 2, v[28:29]
	s_mul_i32 s12, s0, 33
	v_lshl_add_u64 v[34:35], s[12:13], 2, v[28:29]
	s_mul_i32 s12, s0, 34
	v_lshl_add_u64 v[36:37], s[12:13], 2, v[28:29]
	s_mul_i32 s12, s0, 35
	v_lshl_add_u64 v[38:39], s[12:13], 2, v[28:29]
	s_mul_i32 s12, s0, 36
	v_lshl_add_u64 v[40:41], s[12:13], 2, v[28:29]
	s_mul_i32 s12, s0, 37
	v_lshl_add_u64 v[42:43], s[12:13], 2, v[28:29]
	s_mul_i32 s12, s0, 38
	v_lshl_add_u64 v[44:45], s[12:13], 2, v[28:29]
	s_mul_i32 s12, s0, 39
	v_lshl_add_u64 v[80:81], s[12:13], 2, v[28:29]
	s_mul_i32 s12, s0, 40
	global_load_dword v77, v[32:33], off nt
	global_load_dword v52, v[34:35], off nt
	global_load_dword v51, v[36:37], off nt
	global_load_dword v50, v[38:39], off nt
	global_load_dword v49, v[40:41], off nt
	global_load_dword v48, v[42:43], off nt
	global_load_dword v47, v[44:45], off nt
	global_load_dword v46, v[80:81], off nt
	v_lshl_add_u64 v[32:33], s[12:13], 2, v[28:29]
	s_mul_i32 s12, s0, 41
	v_lshl_add_u64 v[34:35], s[12:13], 2, v[28:29]
	s_mul_i32 s12, s0, 42
	v_lshl_add_u64 v[36:37], s[12:13], 2, v[28:29]
	s_mul_i32 s12, s0, 43
	v_lshl_add_u64 v[38:39], s[12:13], 2, v[28:29]
	s_mul_i32 s12, s0, 44
	v_lshl_add_u64 v[40:41], s[12:13], 2, v[28:29]
	s_mul_i32 s12, s0, 45
	v_lshl_add_u64 v[80:81], s[12:13], 2, v[28:29]
	s_mul_i32 s12, s0, 46
	v_lshl_add_u64 v[82:83], s[12:13], 2, v[28:29]
	s_mul_i32 s12, s0, 47
	v_lshl_add_u64 v[84:85], s[12:13], 2, v[28:29]
	s_mul_i32 s12, s0, 48
	global_load_dword v76, v[32:33], off nt
	global_load_dword v45, v[34:35], off nt
	global_load_dword v44, v[36:37], off nt
	global_load_dword v43, v[38:39], off nt
	global_load_dword v42, v[40:41], off nt
	s_nop 0
	global_load_dword v41, v[80:81], off nt
	global_load_dword v40, v[82:83], off nt
	global_load_dword v39, v[84:85], off nt
	v_lshl_add_u64 v[32:33], s[12:13], 2, v[28:29]
	s_mul_i32 s12, s0, 49
	v_lshl_add_u64 v[34:35], s[12:13], 2, v[28:29]
	s_mul_i32 s12, s0, 50
	v_lshl_add_u64 v[36:37], s[12:13], 2, v[28:29]
	s_mul_i32 s12, s0, 51
	v_lshl_add_u64 v[80:81], s[12:13], 2, v[28:29]
	s_mul_i32 s12, s0, 52
	v_lshl_add_u64 v[82:83], s[12:13], 2, v[28:29]
	s_mul_i32 s12, s0, 53
	v_lshl_add_u64 v[84:85], s[12:13], 2, v[28:29]
	s_mul_i32 s12, s0, 54
	v_lshl_add_u64 v[86:87], s[12:13], 2, v[28:29]
	s_mul_i32 s12, s0, 55
	v_lshl_add_u64 v[88:89], s[12:13], 2, v[28:29]
	s_mul_i32 s12, s0, 56
	global_load_dword v75, v[32:33], off nt
	global_load_dword v38, v[34:35], off nt
	s_nop 0
	global_load_dword v37, v[36:37], off nt
	s_nop 0
	global_load_dword v36, v[80:81], off nt
	global_load_dword v35, v[82:83], off nt
	global_load_dword v34, v[84:85], off nt
	global_load_dword v33, v[86:87], off nt
	global_load_dword v32, v[88:89], off nt
	v_lshl_add_u64 v[80:81], s[12:13], 2, v[28:29]
	s_mul_i32 s12, s0, 57
	v_lshl_add_u64 v[82:83], s[12:13], 2, v[28:29]
	s_mul_i32 s12, s0, 58
	v_lshl_add_u64 v[84:85], s[12:13], 2, v[28:29]
	s_mul_i32 s12, s0, 59
	v_lshl_add_u64 v[86:87], s[12:13], 2, v[28:29]
	s_mul_i32 s12, s0, 60
	v_lshl_add_u64 v[88:89], s[12:13], 2, v[28:29]
	s_mul_i32 s12, s0, 61
	v_lshl_add_u64 v[90:91], s[12:13], 2, v[28:29]
	s_mul_i32 s12, s0, 62
	s_mul_i32 s0, s0, 63
	v_lshl_add_u64 v[92:93], s[12:13], 2, v[28:29]
	v_lshl_add_u64 v[94:95], s[0:1], 2, v[28:29]
	global_load_dword v28, v[80:81], off nt
	global_load_dword v17, v[82:83], off nt
	s_nop 0
	global_load_dword v84, v[84:85], off nt
	s_nop 0
	global_load_dword v83, v[86:87], off nt
	global_load_dword v82, v[88:89], off nt
	global_load_dword v81, v[90:91], off nt
	global_load_dword v80, v[92:93], off nt
	global_load_dword v29, v[94:95], off nt
	s_add_u32 s0, s14, s10
	s_addc_u32 s10, s15, s11
	s_and_b64 s[8:9], s[8:9], exec
	s_cselect_b32 s9, s27, s10
	s_cselect_b32 s8, s26, s0

; #define LAS __attribute__((address_space(3)))
; __device__ __forceinline__ TrItem p0_item_of(const Params& p, int it, int lane) {
;     ...
;     const int nblk = N / 64, kb = r / nblk, nb = r % nblk, k0 = 64 * kb, n0 = 64 * nb;
;     TrItem t; t.src = W + (size_t)k0 * N + srccol(map, n0 + lane); t.N = N; t.K = K; t.fp8 = f8;
;     t.dst = f8 ? (bf16*)((unsigned char*)WT + (size_t)n0 * K + k0) : WT + (size_t)n0 * K + k0; return t;
; }
; __device__ __forceinline__ void tr_range(const Params& p, LAS unsigned char* lds, int first, int stride, int end, int lane, int wave) {
;     LAS float* scr = (LAS float*)(lds + wave * (64 * 65 * 4));
;     if (first >= end) return;
;     float ra[64];
;     TrItem cur = p0_item_of(p, first, lane);
; #pragma unroll
;     for (int i = 0; i < 64; ++i) ra[i] = cur.src[(size_t)i * cur.N];
.LBB0_587:
	s_add_u32 s15, s88, s8
	s_addc_u32 s9, s89, s9
	s_lshl_b32 s10, s13, 6
	s_ashr_i32 s11, s10, 31
	v_readlane_b32 s23, v253, 31
	s_mul_i32 s13, s11, s0
	s_mul_hi_u32 s16, s10, s0
	s_sub_i32 s1, s97, s14
	s_mul_i32 s8, s23, 0x4100
	s_add_i32 s17, s16, s13
	s_mul_i32 s16, s10, s0
	s_lshl_b32 s20, s1, 3
	s_add_i32 s8, s8, 0
	s_lshl_b64 s[16:17], s[16:17], 2
	s_add_u32 s6, s6, s16
	s_addc_u32 s7, s7, s17
	v_ashrrev_i32_e32 v3, 31, v2
	v_lshl_add_u64 v[2:3], v[2:3], 2, s[6:7]
	s_mul_hi_i32 s7, s12, s19
	s_mul_i32 s6, s12, s19
	s_lshl_b64 s[12:13], s[6:7], 1
	s_add_u32 s16, s15, s12
	s_addc_u32 s17, s9, s13
	s_lshl_b64 s[12:13], s[10:11], 1
	s_add_u32 s12, s16, s12
	s_addc_u32 s13, s17, s13
	s_add_u32 s6, s15, s6
	s_addc_u32 s7, s9, s7
	s_add_u32 s6, s6, s10
	s_addc_u32 s7, s7, s11
	s_mov_b32 s1, 0
	s_and_b64 s[2:3], s[2:3], exec
	s_cselect_b32 s3, s13, s7
	s_cselect_b32 s2, s12, s6
	s_mul_i32 s6, s0, 63
	s_mov_b32 s7, s1
	v_lshl_add_u64 v[4:5], s[6:7], 2, v[2:3]
	s_mul_i32 s6, s0, 62
	v_lshl_add_u64 v[6:7], s[6:7], 2, v[2:3]
	s_mul_i32 s6, s0, 61
	v_lshl_add_u64 v[8:9], s[6:7], 2, v[2:3]
	s_mul_i32 s6, s0, 60
	v_lshl_add_u64 v[10:11], s[6:7], 2, v[2:3]
	s_mul_i32 s6, s0, 59
	v_lshl_add_u64 v[12:13], s[6:7], 2, v[2:3]
	s_mul_i32 s6, s0, 58
	v_lshl_add_u64 v[14:15], s[6:7], 2, v[2:3]
	s_mul_i32 s6, s0, 57
	v_lshl_add_u64 v[16:17], s[6:7], 2, v[2:3]
	s_mul_i32 s6, s0, 56
	v_lshl_add_u64 v[18:19], s[6:7], 2, v[2:3]
	s_mul_i32 s6, s0, 55
	v_lshl_add_u64 v[20:21], s[6:7], 2, v[2:3]
	s_mul_i32 s6, s0, 54
	v_lshl_add_u64 v[22:23], s[6:7], 2, v[2:3]
	s_mul_i32 s6, s0, 53
	v_lshl_add_u64 v[24:25], s[6:7], 2, v[2:3]
	s_mul_i32 s6, s0, 52
	v_lshl_add_u64 v[26:27], s[6:7], 2, v[2:3]
	s_mul_i32 s6, s0, 51
	v_lshl_add_u64 v[30:31], s[6:7], 2, v[2:3]
	s_mul_i32 s6, s0, 50
	v_lshl_add_u64 v[38:39], s[6:7], 2, v[2:3]
	s_mul_i32 s6, s0, 49
	v_lshl_add_u64 v[40:41], s[6:7], 2, v[2:3]
	s_mul_i32 s6, s0, 48
	global_load_dword v28, v[18:19], off nt
	global_load_dword v32, v[20:21], off nt
	global_load_dword v33, v[22:23], off nt
	global_load_dword v34, v[24:25], off nt
	global_load_dword v35, v[26:27], off nt
	global_load_dword v36, v[30:31], off nt
	global_load_dword v37, v[38:39], off nt
	s_nop 0
	global_load_dword v38, v[40:41], off nt
	v_lshl_add_u64 v[18:19], s[6:7], 2, v[2:3]
	s_mul_i32 s6, s0, 47
	v_lshl_add_u64 v[20:21], s[6:7], 2, v[2:3]
	s_mul_i32 s6, s0, 46
	v_lshl_add_u64 v[22:23], s[6:7], 2, v[2:3]
	s_mul_i32 s6, s0, 45
	v_lshl_add_u64 v[24:25], s[6:7], 2, v[2:3]
	s_mul_i32 s6, s0, 44
	v_lshl_add_u64 v[26:27], s[6:7], 2, v[2:3]
	s_mul_i32 s6, s0, 43
	v_lshl_add_u64 v[30:31], s[6:7], 2, v[2:3]
	s_mul_i32 s6, s0, 42
	v_lshl_add_u64 v[44:45], s[6:7], 2, v[2:3]
	s_mul_i32 s6, s0, 41
	v_lshl_add_u64 v[46:47], s[6:7], 2, v[2:3]
	s_mul_i32 s6, s0, 40
	global_load_dword v75, v[18:19], off nt
	global_load_dword v39, v[20:21], off nt
	global_load_dword v40, v[22:23], off nt
	global_load_dword v41, v[24:25], off nt
	global_load_dword v42, v[26:27], off nt
	global_load_dword v43, v[30:31], off nt
	s_nop 0
	global_load_dword v44, v[44:45], off nt
	s_nop 0
	global_load_dword v45, v[46:47], off nt
	v_lshl_add_u64 v[18:19], s[6:7], 2, v[2:3]
	s_mul_i32 s6, s0, 39
	v_lshl_add_u64 v[20:21], s[6:7], 2, v[2:3]
	s_mul_i32 s6, s0, 38
	v_lshl_add_u64 v[22:23], s[6:7], 2, v[2:3]
	s_mul_i32 s6, s0, 37
	v_lshl_add_u64 v[24:25], s[6:7], 2, v[2:3]
	s_mul_i32 s6, s0, 36
	v_lshl_add_u64 v[26:27], s[6:7], 2, v[2:3]
	s_mul_i32 s6, s0, 35
	v_lshl_add_u64 v[30:31], s[6:7], 2, v[2:3]
	s_mul_i32 s6, s0, 34
	v_lshl_add_u64 v[52:53], s[6:7], 2, v[2:3]
	s_mul_i32 s6, s0, 33
	v_lshl_add_u64 v[54:55], s[6:7], 2, v[2:3]
	s_lshl_b32 s6, s0, 5
	global_load_dword v76, v[18:19], off nt
	global_load_dword v46, v[20:21], off nt
	global_load_dword v47, v[22:23], off nt
	global_load_dword v48, v[24:25], off nt
	global_load_dword v49, v[26:27], off nt
	global_load_dword v50, v[30:31], off nt
	global_load_dword v51, v[52:53], off nt
	s_nop 0
	global_load_dword v52, v[54:55], off nt
	v_lshl_add_u64 v[18:19], s[6:7], 2, v[2:3]
	s_mul_i32 s6, s0, 31
	v_lshl_add_u64 v[20:21], s[6:7], 2, v[2:3]
	s_mul_i32 s6, s0, 30
	v_lshl_add_u64 v[22:23], s[6:7], 2, v[2:3]
	s_mul_i32 s6, s0, 29
	v_lshl_add_u64 v[24:25], s[6:7], 2, v[2:3]
	s_mul_i32 s6, s0, 28
	v_lshl_add_u64 v[26:27], s[6:7], 2, v[2:3]
	s_mul_i32 s6, s0, 27
	v_lshl_add_u64 v[30:31], s[6:7], 2, v[2:3]
	s_mul_i32 s6, s0, 26
	v_lshl_add_u64 v[58:59], s[6:7], 2, v[2:3]
	s_mul_i32 s6, s0, 25
	v_lshl_add_u64 v[60:61], s[6:7], 2, v[2:3]
	s_mul_i32 s6, s0, 24
	global_load_dword v77, v[18:19], off nt
	global_load_dword v53, v[20:21], off nt
	global_load_dword v54, v[22:23], off nt
	global_load_dword v55, v[24:25], off nt
	global_load_dword v56, v[26:27], off nt
; #define LAS __attribute__((address_space(3)))
; #define LDS_WAIT() asm volatile("s_waitcnt lgkmcnt(0)" ::: "memory")
; __device__ __forceinline__ void tr_range(const Params& p, LAS unsigned char* lds, int first, int stride, int end, int lane, int wave) {
;     LAS float* scr = (LAS float*)(lds + wave * (64 * 65 * 4));
;     if (first >= end) return;
;     float ra[64];
;     TrItem cur = p0_item_of(p, first, lane);
; #pragma unroll
;     for (int i = 0; i < 64; ++i) ra[i] = cur.src[(size_t)i * cur.N];
; #pragma unroll 1
;     for (int it = first; it < end; it += stride) {
; #pragma unroll
;         for (int i = 0; i < 64; ++i) scr[i * 65 + lane] = ra[i];
;         const bool more = it + stride < end;
;         TrItem nxt = cur;
;         if (more) { nxt = p0_item_of(p, it + stride, lane);
; #pragma unroll
;             for (int i = 0; i < 64; ++i) ra[i] = nxt.src[(size_t)i * nxt.N]; }
;         LDS_WAIT(); asm volatile("" ::: "memory");
;         if (cur.fp8) {
;             const int c = lane & 3;
; #pragma unroll
	global_load_dword v57, v[30:31], off nt
	s_nop 0
	global_load_dword v58, v[58:59], off nt
	s_nop 0
	global_load_dword v59, v[60:61], off nt
	v_lshl_add_u64 v[18:19], s[6:7], 2, v[2:3]
	s_mul_i32 s6, s0, 23
	v_lshl_add_u64 v[20:21], s[6:7], 2, v[2:3]
	s_mul_i32 s6, s0, 22
	v_lshl_add_u64 v[22:23], s[6:7], 2, v[2:3]
	s_mul_i32 s6, s0, 21
	v_lshl_add_u64 v[24:25], s[6:7], 2, v[2:3]
	s_mul_i32 s6, s0, 20
	v_lshl_add_u64 v[26:27], s[6:7], 2, v[2:3]
	s_mul_i32 s6, s0, 19
	v_lshl_add_u64 v[30:31], s[6:7], 2, v[2:3]
	s_mul_i32 s6, s0, 18
	v_lshl_add_u64 v[66:67], s[6:7], 2, v[2:3]
	s_mul_i32 s6, s0, 17
	v_lshl_add_u64 v[68:69], s[6:7], 2, v[2:3]
	s_lshl_b32 s6, s0, 4
	global_load_dword v78, v[18:19], off nt
	global_load_dword v60, v[20:21], off nt
	global_load_dword v61, v[22:23], off nt
	global_load_dword v62, v[24:25], off nt
	global_load_dword v63, v[26:27], off nt
	global_load_dword v64, v[30:31], off nt
	global_load_dword v65, v[66:67], off nt
	s_nop 0
	global_load_dword v66, v[68:69], off nt
	v_lshl_add_u64 v[18:19], s[6:7], 2, v[2:3]
	s_mul_i32 s6, s0, 15
	v_lshl_add_u64 v[20:21], s[6:7], 2, v[2:3]
	s_mul_i32 s6, s0, 14
	v_lshl_add_u64 v[22:23], s[6:7], 2, v[2:3]
	s_mul_i32 s6, s0, 13
	v_lshl_add_u64 v[24:25], s[6:7], 2, v[2:3]
	s_mul_i32 s6, s0, 12
	v_lshl_add_u64 v[26:27], s[6:7], 2, v[2:3]
	s_mul_i32 s6, s0, 11
	v_lshl_add_u64 v[30:31], s[6:7], 2, v[2:3]
	s_mul_i32 s6, s0, 10
	v_lshl_add_u64 v[72:73], s[6:7], 2, v[2:3]
	s_mul_i32 s6, s0, 9
	v_lshl_add_u64 v[80:81], s[6:7], 2, v[2:3]
	s_lshl_b32 s6, s0, 3
	global_load_dword v79, v[18:19], off nt
	global_load_dword v67, v[20:21], off nt
	global_load_dword v68, v[22:23], off nt
	global_load_dword v69, v[24:25], off nt
	global_load_dword v70, v[26:27], off nt
	global_load_dword v71, v[30:31], off nt
	s_nop 0
	global_load_dword v72, v[72:73], off nt
	s_nop 0
	global_load_dword v73, v[80:81], off nt
	v_lshl_add_u64 v[18:19], s[6:7], 2, v[2:3]
	s_mul_i32 s6, s0, 7
	v_lshl_add_u64 v[20:21], s[6:7], 2, v[2:3]
	s_mul_i32 s6, s0, 6
	v_lshl_add_u64 v[22:23], s[6:7], 2, v[2:3]
	s_mul_i32 s6, s0, 5
	v_lshl_add_u64 v[24:25], s[6:7], 2, v[2:3]
	s_lshl_b32 s6, s0, 2
	v_lshl_add_u64 v[26:27], s[6:7], 2, v[2:3]
	s_mul_i32 s6, s0, 3
	v_lshl_add_u64 v[30:31], s[6:7], 2, v[2:3]
	s_lshl_b32 s6, s0, 1
	v_lshl_add_u64 v[80:81], s[6:7], 2, v[2:3]
	v_lshl_add_u64 v[82:83], s[0:1], 2, v[2:3]
	global_load_dword v74, v[18:19], off nt
	s_nop 0
	global_load_dword v19, v[20:21], off nt
	s_nop 0
	global_load_dword v21, v[22:23], off nt
	s_nop 0
	global_load_dword v23, v[24:25], off nt
	s_nop 0
	global_load_dword v25, v[26:27], off nt
	s_nop 0
	global_load_dword v27, v[30:31], off nt
	s_nop 0
	global_load_dword v30, v[80:81], off nt
	global_load_dword v31, v[82:83], off nt
	global_load_dword v29, v[4:5], off nt
	s_nop 0
	global_load_dword v80, v[6:7], off nt
	global_load_dword v81, v[8:9], off nt
	global_load_dword v82, v[10:11], off nt
	global_load_dword v83, v[12:13], off nt
	global_load_dword v84, v[14:15], off nt
	s_nop 0
	global_load_dword v17, v[16:17], off nt
	s_nop 0
	global_load_dword v15, v[2:3], off nt
	v_readlane_b32 s36, v253, 10
	v_readlane_b32 s48, v253, 22
	v_readlane_b32 s49, v253, 23
	v_lshlrev_b32_e32 v4, 3, v0
	v_readlane_b32 s50, v253, 24
	v_readlane_b32 s51, v253, 25
	s_mov_b64 s[24:25], s[48:49]
	v_lshrrev_b32_e32 v6, 3, v1
	v_and_b32_e32 v4, 56, v4
	s_mov_b64 s[26:27], s[50:51]
	v_mul_u32_u24_e32 v8, 0x104, v130
	v_mul_u32_u24_e32 v11, 0x104, v4
	v_and_b32_e32 v9, 60, v1
	v_lshlrev_b32_e32 v13, 2, v6
	s_add_u32 s6, s26, 0x5800000
	v_lshl_add_u32 v3, v1, 2, s8
	v_add3_u32 v9, s8, v8, v9
	v_add3_u32 v11, s8, v11, v13
	s_addc_u32 s7, s27, 0
	s_lshl_b32 s0, s97, 3
	s_lshl_b32 s8, s14, 4
	s_sub_i32 s22, s0, s8
	s_lshl_b32 s0, s86, 3
	s_addk_i32 s0, 0xeb80
	v_lshrrev_b32_e32 v2, 2, v1
	v_mov_b32_e32 v5, 0
	s_add_i32 s23, s23, s0
	s_lshl_b32 s0, s14, 3
	v_and_b32_e32 v7, 31, v0
	v_mov_b32_e32 v131, v5
	v_or_b32_e32 v8, 16, v2
	v_or_b32_e32 v10, 32, v2
	v_or_b32_e32 v12, 48, v2
	v_or_b32_e32 v14, 8, v6
	v_or_b32_e32 v16, 16, v6
	v_or_b32_e32 v18, 24, v6
	v_or_b32_e32 v20, 32, v6
	v_or_b32_e32 v22, 40, v6
	v_or_b32_e32 v24, 48, v6
	v_or_b32_e32 v26, 56, v6
	s_sub_i32 s24, 0x4200, s0
	s_mov_b32 s25, 0xc3e00000
	v_lshlrev_b32_e32 v4, 1, v4
	v_mov_b32_e32 v13, 0x43e00000
	s_mov_b32 s16, s21
	s_mov_b64 s[8:9], s[2:3]
	s_mov_b32 s17, s19
	v_readlane_b32 s37, v253, 11
	v_readlane_b32 s38, v253, 12
	v_readlane_b32 s39, v253, 13
	v_readlane_b32 s40, v253, 14
	v_readlane_b32 s41, v253, 15
	v_readlane_b32 s42, v253, 16
	v_readlane_b32 s43, v253, 17
	v_readlane_b32 s44, v253, 18
	v_readlane_b32 s45, v253, 19
	v_readlane_b32 s46, v253, 20
	v_readlane_b32 s47, v253, 21
	s_branch .LBB0_590

; #define LAS __attribute__((address_space(3)))
; __device__ __forceinline__ TrItem p0_item_of(const Params& p, int it, int lane) {
;     ...
;     const int nblk = N / 64, kb = r / nblk, nb = r % nblk, k0 = 64 * kb, n0 = 64 * nb;
;     TrItem t; t.src = W + (size_t)k0 * N + srccol(map, n0 + lane); t.N = N; t.K = K; t.fp8 = f8;
;     t.dst = f8 ? (bf16*)((unsigned char*)WT + (size_t)n0 * K + k0) : WT + (size_t)n0 * K + k0; return t;
; }
; __device__ __forceinline__ void tr_range(const Params& p, LAS unsigned char* lds, int first, int stride, int end, int lane, int wave) {
;     LAS float* scr = (LAS float*)(lds + wave * (64 * 65 * 4));
;     if (first >= end) return;
;     float ra[64];
;     TrItem cur = p0_item_of(p, first, lane);
; #pragma unroll
;     for (int i = 0; i < 64; ++i) ra[i] = cur.src[(size_t)i * cur.N];
.LBB0_1162:
	s_lshl_b32 s16, s15, 6
	s_ashr_i32 s17, s16, 31
	v_readlane_b32 s34, v253, 31
	s_mul_i32 s11, s17, s0
	s_mul_hi_u32 s15, s16, s0
	s_sub_i32 s1, s97, s30
	s_mul_i32 s10, s34, 0x4100
	s_add_i32 s19, s15, s11
	s_mul_i32 s18, s16, s0
	s_lshl_b32 s43, s1, 3
	s_add_i32 s10, s10, 0
	s_lshl_b64 s[18:19], s[18:19], 2
	s_add_u32 s2, s2, s18
	s_addc_u32 s3, s3, s19
	v_ashrrev_i32_e32 v3, 31, v2
	v_lshl_add_u64 v[2:3], v[2:3], 2, s[2:3]
	s_ashr_i32 s2, s14, 31
	s_mul_hi_u32 s3, s14, s42
	s_mul_i32 s2, s2, s42
	s_add_i32 s3, s3, s2
	s_mul_i32 s2, s14, s42
	s_lshl_b64 s[14:15], s[2:3], 1
	s_add_u32 s11, s4, s14
	s_addc_u32 s18, s5, s15
	s_lshl_b64 s[14:15], s[16:17], 1
	s_add_u32 s11, s11, s14
	s_addc_u32 s14, s18, s15
	s_add_u32 s2, s4, s2
	s_addc_u32 s3, s5, s3
	s_add_u32 s4, s2, s16
	s_addc_u32 s5, s3, s17
	s_mov_b32 s1, 0
	s_and_b64 s[2:3], s[8:9], exec
	s_cselect_b32 s3, s14, s5
	s_cselect_b32 s2, s11, s4
	s_mul_i32 s4, s0, 63
	s_mov_b32 s5, s1
	v_lshl_add_u64 v[4:5], s[4:5], 2, v[2:3]
	s_mul_i32 s4, s0, 62
	v_lshl_add_u64 v[6:7], s[4:5], 2, v[2:3]
	s_mul_i32 s4, s0, 61
	v_lshl_add_u64 v[8:9], s[4:5], 2, v[2:3]
	s_mul_i32 s4, s0, 60
	v_lshl_add_u64 v[10:11], s[4:5], 2, v[2:3]
	s_mul_i32 s4, s0, 59
	v_lshl_add_u64 v[12:13], s[4:5], 2, v[2:3]
	s_mul_i32 s4, s0, 58
	v_lshl_add_u64 v[14:15], s[4:5], 2, v[2:3]
	s_mul_i32 s4, s0, 57
	v_lshl_add_u64 v[16:17], s[4:5], 2, v[2:3]
	s_mul_i32 s4, s0, 56
	v_lshl_add_u64 v[18:19], s[4:5], 2, v[2:3]
	s_mul_i32 s4, s0, 55
	v_lshl_add_u64 v[20:21], s[4:5], 2, v[2:3]
	s_mul_i32 s4, s0, 54
	v_lshl_add_u64 v[22:23], s[4:5], 2, v[2:3]
	s_mul_i32 s4, s0, 53
	v_lshl_add_u64 v[24:25], s[4:5], 2, v[2:3]
	s_mul_i32 s4, s0, 52
	v_lshl_add_u64 v[26:27], s[4:5], 2, v[2:3]
	s_mul_i32 s4, s0, 51
	v_lshl_add_u64 v[28:29], s[4:5], 2, v[2:3]
	s_mul_i32 s4, s0, 50
	v_lshl_add_u64 v[30:31], s[4:5], 2, v[2:3]
	s_mul_i32 s4, s0, 49
	v_lshl_add_u64 v[32:33], s[4:5], 2, v[2:3]
	s_mul_i32 s4, s0, 48
	global_load_dword v80, v[18:19], off nt
	global_load_dword v79, v[20:21], off nt
	global_load_dword v77, v[22:23], off nt
	global_load_dword v75, v[24:25], off nt
	global_load_dword v74, v[26:27], off nt
	global_load_dword v72, v[28:29], off nt
	global_load_dword v69, v[30:31], off nt
	global_load_dword v67, v[32:33], off nt
	v_lshl_add_u64 v[18:19], s[4:5], 2, v[2:3]
	s_mul_i32 s4, s0, 47
	v_lshl_add_u64 v[20:21], s[4:5], 2, v[2:3]
	s_mul_i32 s4, s0, 46
	v_lshl_add_u64 v[22:23], s[4:5], 2, v[2:3]
	s_mul_i32 s4, s0, 45
	v_lshl_add_u64 v[24:25], s[4:5], 2, v[2:3]
	s_mul_i32 s4, s0, 44
	v_lshl_add_u64 v[26:27], s[4:5], 2, v[2:3]
	s_mul_i32 s4, s0, 43
	v_lshl_add_u64 v[28:29], s[4:5], 2, v[2:3]
	s_mul_i32 s4, s0, 42
	v_lshl_add_u64 v[30:31], s[4:5], 2, v[2:3]
	s_mul_i32 s4, s0, 41
	v_lshl_add_u64 v[32:33], s[4:5], 2, v[2:3]
	s_mul_i32 s4, s0, 40
	global_load_dword v78, v[18:19], off nt
	global_load_dword v76, v[20:21], off nt
	global_load_dword v71, v[22:23], off nt
	global_load_dword v68, v[24:25], off nt
	global_load_dword v66, v[26:27], off nt
	global_load_dword v64, v[28:29], off nt
	global_load_dword v61, v[30:31], off nt
	global_load_dword v59, v[32:33], off nt
	v_lshl_add_u64 v[18:19], s[4:5], 2, v[2:3]
	s_mul_i32 s4, s0, 39
	v_lshl_add_u64 v[20:21], s[4:5], 2, v[2:3]
	s_mul_i32 s4, s0, 38
	v_lshl_add_u64 v[22:23], s[4:5], 2, v[2:3]
	s_mul_i32 s4, s0, 37
	v_lshl_add_u64 v[24:25], s[4:5], 2, v[2:3]
	s_mul_i32 s4, s0, 36
	v_lshl_add_u64 v[26:27], s[4:5], 2, v[2:3]
	s_mul_i32 s4, s0, 35
	v_lshl_add_u64 v[28:29], s[4:5], 2, v[2:3]
	s_mul_i32 s4, s0, 34
	v_lshl_add_u64 v[30:31], s[4:5], 2, v[2:3]
	s_mul_i32 s4, s0, 33
	v_lshl_add_u64 v[32:33], s[4:5], 2, v[2:3]
	s_lshl_b32 s4, s0, 5
	global_load_dword v73, v[18:19], off nt
	global_load_dword v70, v[20:21], off nt
	global_load_dword v63, v[22:23], off nt
	global_load_dword v60, v[24:25], off nt
	global_load_dword v58, v[26:27], off nt
	global_load_dword v56, v[28:29], off nt
	global_load_dword v53, v[30:31], off nt
	global_load_dword v51, v[32:33], off nt
	v_lshl_add_u64 v[18:19], s[4:5], 2, v[2:3]
	s_mul_i32 s4, s0, 31
	v_lshl_add_u64 v[20:21], s[4:5], 2, v[2:3]
	s_mul_i32 s4, s0, 30
	v_lshl_add_u64 v[22:23], s[4:5], 2, v[2:3]
	s_mul_i32 s4, s0, 29
	v_lshl_add_u64 v[24:25], s[4:5], 2, v[2:3]
	s_mul_i32 s4, s0, 28
	v_lshl_add_u64 v[26:27], s[4:5], 2, v[2:3]
	s_mul_i32 s4, s0, 27
	v_lshl_add_u64 v[28:29], s[4:5], 2, v[2:3]
	s_mul_i32 s4, s0, 26
	v_lshl_add_u64 v[30:31], s[4:5], 2, v[2:3]
	s_mul_i32 s4, s0, 25
	v_lshl_add_u64 v[32:33], s[4:5], 2, v[2:3]
	s_mul_i32 s4, s0, 24
	global_load_dword v65, v[18:19], off nt
	global_load_dword v62, v[20:21], off nt
	global_load_dword v55, v[22:23], off nt
	global_load_dword v52, v[24:25], off nt
	global_load_dword v50, v[26:27], off nt
	global_load_dword v48, v[28:29], off nt
	global_load_dword v45, v[30:31], off nt
	global_load_dword v43, v[32:33], off nt
	v_lshl_add_u64 v[18:19], s[4:5], 2, v[2:3]
	s_mul_i32 s4, s0, 23
	v_lshl_add_u64 v[20:21], s[4:5], 2, v[2:3]
	s_mul_i32 s4, s0, 22
	v_lshl_add_u64 v[22:23], s[4:5], 2, v[2:3]
	s_mul_i32 s4, s0, 21
	v_lshl_add_u64 v[24:25], s[4:5], 2, v[2:3]
	s_mul_i32 s4, s0, 20
	v_lshl_add_u64 v[26:27], s[4:5], 2, v[2:3]
	s_mul_i32 s4, s0, 19
	v_lshl_add_u64 v[28:29], s[4:5], 2, v[2:3]
	s_mul_i32 s4, s0, 18
; #define LAS __attribute__((address_space(3)))
; #define LDS_WAIT() asm volatile("s_waitcnt lgkmcnt(0)" ::: "memory")
; __device__ __forceinline__ void tr_range(const Params& p, LAS unsigned char* lds, int first, int stride, int end, int lane, int wave) {
;     LAS float* scr = (LAS float*)(lds + wave * (64 * 65 * 4));
;     if (first >= end) return;
;     float ra[64];
;     TrItem cur = p0_item_of(p, first, lane);
; #pragma unroll
;     for (int i = 0; i < 64; ++i) ra[i] = cur.src[(size_t)i * cur.N];
; #pragma unroll 1
;     for (int it = first; it < end; it += stride) {
; #pragma unroll
;         for (int i = 0; i < 64; ++i) scr[i * 65 + lane] = ra[i];
;         const bool more = it + stride < end;
;         TrItem nxt = cur;
;         if (more) { nxt = p0_item_of(p, it + stride, lane);
; #pragma unroll
;             for (int i = 0; i < 64; ++i) ra[i] = nxt.src[(size_t)i * nxt.N]; }
;         LDS_WAIT(); asm volatile("" ::: "memory");
;         if (cur.fp8) {
;             const int c = lane & 3;
; #pragma unroll
;             for (int j = 0; j < 4; ++j) { const int n = (lane >> 2) + 16 * j; const LAS float* s = scr + (16 * c) * 65 + n;
;                 u32x4 o;
;                 o.x = pk4_fp8(s[0 * 65] * W8_SCALE, s[1 * 65] * W8_SCALE, s[2 * 65] * W8_SCALE, s[3 * 65] * W8_SCALE);
;                 o.y = pk4_fp8(s[4 * 65] * W8_SCALE, s[5 * 65] * W8_SCALE, s[6 * 65] * W8_SCALE, s[7 * 65] * W8_SCALE);
;                 o.z = pk4_fp8(s[8 * 65] * W8_SCALE, s[9 * 65] * W8_SCALE, s[10 * 65] * W8_SCALE, s[11 * 65] * W8_SCALE);
;                 o.w = pk4_fp8(s[12 * 65] * W8_SCALE, s[13 * 65] * W8_SCALE, s[14 * 65] * W8_SCALE, s[15 * 65] * W8_SCALE);
;                 *(u32x4*)((unsigned char*)cur.dst + (size_t)n * cur.K + 16 * c) = o; }
;         } else {
;         const int c = lane & 7;
; #pragma unroll
;         for (int j = 0; j < 8; ++j) { const int n = (lane >> 3) + 8 * j; const LAS float* s = scr + (8 * c) * 65 + n;
	v_lshl_add_u64 v[30:31], s[4:5], 2, v[2:3]
	s_mul_i32 s4, s0, 17
	v_lshl_add_u64 v[32:33], s[4:5], 2, v[2:3]
	s_lshl_b32 s4, s0, 4
	global_load_dword v57, v[18:19], off nt
	global_load_dword v54, v[20:21], off nt
	global_load_dword v47, v[22:23], off nt
	global_load_dword v44, v[24:25], off nt
	global_load_dword v42, v[26:27], off nt
	global_load_dword v41, v[28:29], off nt
	global_load_dword v38, v[30:31], off nt
	global_load_dword v35, v[32:33], off nt
	v_lshl_add_u64 v[18:19], s[4:5], 2, v[2:3]
	s_mul_i32 s4, s0, 15
	v_lshl_add_u64 v[20:21], s[4:5], 2, v[2:3]
	s_mul_i32 s4, s0, 14
	v_lshl_add_u64 v[22:23], s[4:5], 2, v[2:3]
	s_mul_i32 s4, s0, 13
	v_lshl_add_u64 v[24:25], s[4:5], 2, v[2:3]
	s_mul_i32 s4, s0, 12
	v_lshl_add_u64 v[26:27], s[4:5], 2, v[2:3]
	s_mul_i32 s4, s0, 11
	v_lshl_add_u64 v[28:29], s[4:5], 2, v[2:3]
	s_mul_i32 s4, s0, 10
	v_lshl_add_u64 v[30:31], s[4:5], 2, v[2:3]
	s_mul_i32 s4, s0, 9
	v_lshl_add_u64 v[82:83], s[4:5], 2, v[2:3]
	s_lshl_b32 s4, s0, 3
	global_load_dword v49, v[18:19], off nt
	global_load_dword v46, v[20:21], off nt
	global_load_dword v39, v[22:23], off nt
	global_load_dword v36, v[24:25], off nt
	global_load_dword v34, v[26:27], off nt
	global_load_dword v33, v[28:29], off nt
	s_nop 0
	global_load_dword v31, v[30:31], off nt
	s_nop 0
	global_load_dword v27, v[82:83], off nt
	v_lshl_add_u64 v[18:19], s[4:5], 2, v[2:3]
	s_mul_i32 s4, s0, 7
	v_lshl_add_u64 v[20:21], s[4:5], 2, v[2:3]
	s_mul_i32 s4, s0, 6
	v_lshl_add_u64 v[22:23], s[4:5], 2, v[2:3]
	s_mul_i32 s4, s0, 5
	v_lshl_add_u64 v[24:25], s[4:5], 2, v[2:3]
	s_lshl_b32 s4, s0, 2
	v_lshl_add_u64 v[28:29], s[4:5], 2, v[2:3]
	s_mul_i32 s4, s0, 3
	v_lshl_add_u64 v[82:83], s[4:5], 2, v[2:3]
	s_lshl_b32 s4, s0, 1
	v_lshl_add_u64 v[84:85], s[4:5], 2, v[2:3]
	v_lshl_add_u64 v[86:87], s[0:1], 2, v[2:3]
	global_load_dword v40, v[18:19], off nt
	global_load_dword v37, v[20:21], off nt
	global_load_dword v32, v[22:23], off nt
	global_load_dword v30, v[24:25], off nt
	s_nop 0
	global_load_dword v25, v[28:29], off nt
	global_load_dword v23, v[82:83], off nt
	global_load_dword v21, v[84:85], off nt
	global_load_dword v19, v[86:87], off nt
	s_nop 0
	global_load_dword v28, v[4:5], off nt
	global_load_dword v85, v[6:7], off nt
	global_load_dword v84, v[8:9], off nt
	global_load_dword v83, v[10:11], off nt
	global_load_dword v82, v[12:13], off nt
	global_load_dword v81, v[14:15], off nt
	s_nop 0
	global_load_dword v17, v[16:17], off nt
	s_nop 0
	global_load_dword v15, v[2:3], off nt
	v_lshlrev_b32_e32 v4, 3, v0
	v_lshrrev_b32_e32 v6, 3, v1
	v_and_b32_e32 v4, 56, v4
	v_mul_u32_u24_e32 v8, 0x104, v130
	v_mul_u32_u24_e32 v11, 0x104, v4
	v_and_b32_e32 v9, 60, v1
	v_lshlrev_b32_e32 v13, 2, v6
	v_writelane_b32 v252, s68, 24
	v_lshl_add_u32 v3, v1, 2, s10
	v_add3_u32 v9, s10, v8, v9
	v_add3_u32 v11, s10, v11, v13
	v_readlane_b32 s4, v253, 32
	v_writelane_b32 v252, s69, 25
	v_readlane_b32 s5, v253, 33
	s_add_u32 s92, s4, 0x5800000
	v_readlane_b32 s68, v253, 10
	v_readlane_b32 s6, v253, 34
	s_addc_u32 s93, s5, 0
	v_readlane_b32 s80, v253, 22
	v_readlane_b32 s81, v253, 23
	v_readlane_b32 s7, v253, 35
	s_add_u32 s6, s88, 0xe000000
	v_readlane_b32 s82, v253, 24
	v_readlane_b32 s83, v253, 25
	s_mov_b64 s[20:21], s[80:81]
	s_addc_u32 s7, s89, 0
	v_readlane_b32 s74, v253, 16
	s_mov_b64 s[22:23], s[82:83]
	v_readlane_b32 s75, v253, 17
	s_add_u32 s74, s22, 0xb000000
	v_readlane_b32 s76, v253, 18
	s_addc_u32 s75, s23, 0
	v_readlane_b32 s77, v253, 19
	s_add_u32 s76, s88, 0x5c00000
	v_readlane_b32 s78, v253, 20
	s_addc_u32 s77, s89, 0
	v_readlane_b32 s79, v253, 21
	s_add_u32 s78, s4, 0x2c00000
	s_addc_u32 s79, s5, 0
	s_add_u32 s80, s88, 0xca00000
	s_addc_u32 s81, s89, 0
	s_add_u32 s20, s22, 0x5800000
	s_addc_u32 s21, s23, 0
	s_add_u32 s22, s88, 0x12000000
	s_addc_u32 s23, s89, 0
	s_add_u32 s24, s88, 0x10c00000
	s_addc_u32 s25, s89, 0
	s_add_u32 s26, s88, 0xb400000
	s_addc_u32 s27, s89, 0
	s_add_u32 s28, s88, 0x400000
	s_addc_u32 s29, s89, 0
	s_lshl_b32 s0, s97, 3
	s_lshl_b32 s31, s30, 4
	s_sub_i32 s45, s0, s31
	s_lshl_b32 s0, s86, 3
	v_lshrrev_b32_e32 v2, 2, v1
	v_mov_b32_e32 v5, 0
	s_add_i32 s46, s34, s0
	s_lshl_b32 s0, s30, 3
	v_and_b32_e32 v7, 31, v0
	v_mov_b32_e32 v131, v5
	v_or_b32_e32 v8, 16, v2
	v_or_b32_e32 v10, 32, v2
	v_or_b32_e32 v12, 48, v2
	v_or_b32_e32 v14, 8, v6
	v_or_b32_e32 v16, 16, v6
	v_or_b32_e32 v18, 24, v6
	v_or_b32_e32 v20, 32, v6
	v_or_b32_e32 v22, 40, v6
	v_or_b32_e32 v24, 48, v6
	v_or_b32_e32 v26, 56, v6
	v_writelane_b32 v252, s6, 22
	s_sub_i32 s47, 0x4500, s0
	s_mov_b32 s48, 0xc3e00000
	v_lshlrev_b32_e32 v4, 1, v4
	v_mov_b32_e32 v13, 0x43e00000
	s_mov_b32 s50, s44
	s_mov_b64 s[30:31], s[2:3]
	s_mov_b32 s49, s42
	v_readlane_b32 s8, v253, 36
	v_readlane_b32 s9, v253, 37
	v_readlane_b32 s10, v253, 38
	v_readlane_b32 s11, v253, 39
	v_readlane_b32 s12, v253, 40
	v_readlane_b32 s13, v253, 41
	v_readlane_b32 s14, v253, 42
	v_readlane_b32 s15, v253, 43
	v_readlane_b32 s16, v253, 44
	v_readlane_b32 s17, v253, 45
	v_readlane_b32 s18, v253, 46
	v_readlane_b32 s19, v253, 47
	v_writelane_b32 v252, s7, 23
	v_readlane_b32 s69, v253, 11
	v_readlane_b32 s70, v253, 12
	v_readlane_b32 s71, v253, 13
	v_readlane_b32 s72, v253, 14
	v_readlane_b32 s73, v253, 15
	s_branch .LBB0_1165

; __device__ __forceinline__ TrItem p0_item_of(const Params& p, int it, int lane) {
;     ...
;     const int nblk = N / 64, kb = r / nblk, nb = r % nblk, k0 = 64 * kb, n0 = 64 * nb;
;     TrItem t; t.src = W + (size_t)k0 * N + srccol(map, n0 + lane); t.N = N; t.K = K; t.fp8 = f8;
;     t.dst = f8 ? (bf16*)((unsigned char*)WT + (size_t)n0 * K + k0) : WT + (size_t)n0 * K + k0; return t;
; __device__ __forceinline__ void tr_range(const Params& p, LAS unsigned char* lds, int first, int stride, int end, int lane, int wave) {
;     ...
;         const bool more = it + stride < end;
;         TrItem nxt = cur;
;         if (more) { nxt = p0_item_of(p, it + stride, lane);
; #pragma unroll
;             for (int i = 0; i < 64; ++i) ra[i] = nxt.src[(size_t)i * nxt.N]; }
.LBB0_1206:
	s_lshl_b32 s36, s41, 6
	s_ashr_i32 s41, s40, 31
	s_mul_hi_u32 s51, s40, s49
	s_mul_i32 s41, s41, s49
	s_ashr_i32 s37, s36, 31
	s_add_i32 s51, s51, s41
	s_mul_i32 s40, s40, s49
	s_add_u32 s38, s38, s40
	s_addc_u32 s39, s39, s51
	s_add_u32 s68, s38, s40
	s_addc_u32 s51, s39, s51
	s_lshl_b64 s[40:41], s[36:37], 1
	s_add_u32 s40, s68, s40
	s_addc_u32 s41, s51, s41
	s_mul_i32 s51, s37, s0
	s_mul_hi_u32 s68, s36, s0
	s_add_i32 s69, s68, s51
	s_mul_i32 s68, s36, s0
	s_lshl_b64 s[68:69], s[68:69], 2
	s_add_u32 s34, s34, s68
	s_addc_u32 s35, s35, s69
	v_ashrrev_i32_e32 v29, 31, v28
	v_lshl_add_u64 v[28:29], v[28:29], 2, s[34:35]
	v_lshl_add_u64 v[30:31], s[0:1], 2, v[28:29]
	s_lshl_b32 s34, s0, 1
	s_mov_b32 s35, s1
	global_load_dword v15, v[28:29], off nt
	global_load_dword v19, v[30:31], off nt
	v_lshl_add_u64 v[30:31], s[34:35], 2, v[28:29]
	s_mul_i32 s34, s0, 3
	global_load_dword v21, v[30:31], off nt
	v_lshl_add_u64 v[30:31], s[34:35], 2, v[28:29]
	s_lshl_b32 s34, s0, 2
	global_load_dword v23, v[30:31], off nt
	v_lshl_add_u64 v[30:31], s[34:35], 2, v[28:29]
	s_mul_i32 s34, s0, 5
	global_load_dword v25, v[30:31], off nt
	v_lshl_add_u64 v[30:31], s[34:35], 2, v[28:29]
	s_mul_i32 s34, s0, 6
	v_lshl_add_u64 v[32:33], s[34:35], 2, v[28:29]
	s_mul_i32 s34, s0, 7
	v_lshl_add_u64 v[34:35], s[34:35], 2, v[28:29]
	s_lshl_b32 s34, s0, 3
	global_load_dword v30, v[30:31], off nt
	s_nop 0
	global_load_dword v32, v[32:33], off nt
	s_nop 0
	global_load_dword v37, v[34:35], off nt
	v_lshl_add_u64 v[34:35], s[34:35], 2, v[28:29]
	s_mul_i32 s34, s0, 9
	global_load_dword v40, v[34:35], off nt
	v_lshl_add_u64 v[34:35], s[34:35], 2, v[28:29]
	s_mul_i32 s34, s0, 10
	global_load_dword v27, v[34:35], off nt
	v_lshl_add_u64 v[34:35], s[34:35], 2, v[28:29]
	s_mul_i32 s34, s0, 11
	global_load_dword v31, v[34:35], off nt
	v_lshl_add_u64 v[34:35], s[34:35], 2, v[28:29]
	s_mul_i32 s34, s0, 12
	global_load_dword v33, v[34:35], off nt
	v_lshl_add_u64 v[34:35], s[34:35], 2, v[28:29]
	s_mul_i32 s34, s0, 13
	v_lshl_add_u64 v[38:39], s[34:35], 2, v[28:29]
	s_mul_i32 s34, s0, 14
	global_load_dword v34, v[34:35], off nt
	s_nop 0
	global_load_dword v36, v[38:39], off nt
	v_lshl_add_u64 v[38:39], s[34:35], 2, v[28:29]
	s_mul_i32 s34, s0, 15
	v_lshl_add_u64 v[42:43], s[34:35], 2, v[28:29]
	s_lshl_b32 s34, s0, 4
	global_load_dword v39, v[38:39], off nt
	s_nop 0
	global_load_dword v46, v[42:43], off nt
	v_lshl_add_u64 v[42:43], s[34:35], 2, v[28:29]
	s_mul_i32 s34, s0, 17
	global_load_dword v49, v[42:43], off nt
	v_lshl_add_u64 v[42:43], s[34:35], 2, v[28:29]
	s_mul_i32 s34, s0, 18
	global_load_dword v35, v[42:43], off nt
	v_lshl_add_u64 v[42:43], s[34:35], 2, v[28:29]
	s_mul_i32 s34, s0, 19
	global_load_dword v38, v[42:43], off nt
	v_lshl_add_u64 v[42:43], s[34:35], 2, v[28:29]
	s_mul_i32 s34, s0, 20
	global_load_dword v41, v[42:43], off nt
	v_lshl_add_u64 v[42:43], s[34:35], 2, v[28:29]
	s_mul_i32 s34, s0, 21
	v_lshl_add_u64 v[44:45], s[34:35], 2, v[28:29]
	s_mul_i32 s34, s0, 22
	v_lshl_add_u64 v[50:51], s[34:35], 2, v[28:29]
	s_mul_i32 s34, s0, 23
	global_load_dword v42, v[42:43], off nt
	s_nop 0
	global_load_dword v44, v[44:45], off nt
	s_nop 0
	global_load_dword v47, v[50:51], off nt
	v_lshl_add_u64 v[50:51], s[34:35], 2, v[28:29]
	s_mul_i32 s34, s0, 24
	global_load_dword v54, v[50:51], off nt
	v_lshl_add_u64 v[50:51], s[34:35], 2, v[28:29]
	s_mul_i32 s34, s0, 25
	global_load_dword v57, v[50:51], off nt
	v_lshl_add_u64 v[50:51], s[34:35], 2, v[28:29]
	s_mul_i32 s34, s0, 26
	global_load_dword v43, v[50:51], off nt
	v_lshl_add_u64 v[50:51], s[34:35], 2, v[28:29]
	s_mul_i32 s34, s0, 27
	global_load_dword v45, v[50:51], off nt
	v_lshl_add_u64 v[50:51], s[34:35], 2, v[28:29]
	s_mul_i32 s34, s0, 28
	global_load_dword v48, v[50:51], off nt
	v_lshl_add_u64 v[50:51], s[34:35], 2, v[28:29]
	s_mul_i32 s34, s0, 29
	v_lshl_add_u64 v[52:53], s[34:35], 2, v[28:29]
	s_mul_i32 s34, s0, 30
	v_lshl_add_u64 v[58:59], s[34:35], 2, v[28:29]
	s_mul_i32 s34, s0, 31
; __device__ __forceinline__ TrItem p0_item_of(const Params& p, int it, int lane) {
;     ...
;     t.dst = f8 ? (bf16*)((unsigned char*)WT + (size_t)n0 * K + k0) : WT + (size_t)n0 * K + k0; return t;
; __device__ __forceinline__ void tr_range(const Params& p, LAS unsigned char* lds, int first, int stride, int end, int lane, int wave) {
;     ...
;         if (more) { nxt = p0_item_of(p, it + stride, lane);
; #pragma unroll
;             for (int i = 0; i < 64; ++i) ra[i] = nxt.src[(size_t)i * nxt.N]; }
	global_load_dword v50, v[50:51], off nt
	s_nop 0
	global_load_dword v52, v[52:53], off nt
	s_nop 0
	global_load_dword v55, v[58:59], off nt
	v_lshl_add_u64 v[58:59], s[34:35], 2, v[28:29]
	s_lshl_b32 s34, s0, 5
	global_load_dword v62, v[58:59], off nt
	v_lshl_add_u64 v[58:59], s[34:35], 2, v[28:29]
	s_mul_i32 s34, s0, 33
	global_load_dword v65, v[58:59], off nt
	v_lshl_add_u64 v[58:59], s[34:35], 2, v[28:29]
	s_mul_i32 s34, s0, 34
	global_load_dword v51, v[58:59], off nt
	v_lshl_add_u64 v[58:59], s[34:35], 2, v[28:29]
	s_mul_i32 s34, s0, 35
	global_load_dword v53, v[58:59], off nt
	v_lshl_add_u64 v[58:59], s[34:35], 2, v[28:29]
	s_mul_i32 s34, s0, 36
	global_load_dword v56, v[58:59], off nt
	v_lshl_add_u64 v[58:59], s[34:35], 2, v[28:29]
	s_mul_i32 s34, s0, 37
	v_lshl_add_u64 v[60:61], s[34:35], 2, v[28:29]
	s_mul_i32 s34, s0, 38
	v_lshl_add_u64 v[66:67], s[34:35], 2, v[28:29]
	s_mul_i32 s34, s0, 39
	global_load_dword v58, v[58:59], off nt
	s_nop 0
	global_load_dword v60, v[60:61], off nt
	s_nop 0
	global_load_dword v63, v[66:67], off nt
	v_lshl_add_u64 v[66:67], s[34:35], 2, v[28:29]
	s_mul_i32 s34, s0, 40
	global_load_dword v70, v[66:67], off nt
	v_lshl_add_u64 v[66:67], s[34:35], 2, v[28:29]
	s_mul_i32 s34, s0, 41
	global_load_dword v73, v[66:67], off nt
	v_lshl_add_u64 v[66:67], s[34:35], 2, v[28:29]
	s_mul_i32 s34, s0, 42
	global_load_dword v59, v[66:67], off nt
	v_lshl_add_u64 v[66:67], s[34:35], 2, v[28:29]
	s_mul_i32 s34, s0, 43
	global_load_dword v61, v[66:67], off nt
	v_lshl_add_u64 v[66:67], s[34:35], 2, v[28:29]
	s_mul_i32 s34, s0, 44
	global_load_dword v64, v[66:67], off nt
	v_lshl_add_u64 v[66:67], s[34:35], 2, v[28:29]
	s_mul_i32 s34, s0, 45
	v_lshl_add_u64 v[68:69], s[34:35], 2, v[28:29]
	s_mul_i32 s34, s0, 46
	v_lshl_add_u64 v[74:75], s[34:35], 2, v[28:29]
	s_mul_i32 s34, s0, 47
	global_load_dword v66, v[66:67], off nt
	s_nop 0
	global_load_dword v68, v[68:69], off nt
	s_nop 0
	global_load_dword v71, v[74:75], off nt
	v_lshl_add_u64 v[74:75], s[34:35], 2, v[28:29]
	s_mul_i32 s34, s0, 48
	global_load_dword v76, v[74:75], off nt
	v_lshl_add_u64 v[74:75], s[34:35], 2, v[28:29]
	s_mul_i32 s34, s0, 49
	global_load_dword v78, v[74:75], off nt
	v_lshl_add_u64 v[74:75], s[34:35], 2, v[28:29]
	s_mul_i32 s34, s0, 50
	global_load_dword v67, v[74:75], off nt
	v_lshl_add_u64 v[74:75], s[34:35], 2, v[28:29]
	s_mul_i32 s34, s0, 51
	global_load_dword v69, v[74:75], off nt
	v_lshl_add_u64 v[74:75], s[34:35], 2, v[28:29]
	s_mul_i32 s34, s0, 52
	global_load_dword v72, v[74:75], off nt
	v_lshl_add_u64 v[74:75], s[34:35], 2, v[28:29]
	s_mul_i32 s34, s0, 53
	v_lshl_add_u64 v[80:81], s[34:35], 2, v[28:29]
	s_mul_i32 s34, s0, 54
	global_load_dword v74, v[74:75], off nt
	s_nop 0
	global_load_dword v75, v[80:81], off nt
	v_lshl_add_u64 v[80:81], s[34:35], 2, v[28:29]
	s_mul_i32 s34, s0, 55
	global_load_dword v77, v[80:81], off nt
	v_lshl_add_u64 v[80:81], s[34:35], 2, v[28:29]
	s_mul_i32 s34, s0, 56
	global_load_dword v79, v[80:81], off nt
	v_lshl_add_u64 v[80:81], s[34:35], 2, v[28:29]
	s_mul_i32 s34, s0, 57
	v_lshl_add_u64 v[82:83], s[34:35], 2, v[28:29]
	s_mul_i32 s34, s0, 58
	global_load_dword v80, v[80:81], off nt
	s_nop 0
	global_load_dword v17, v[82:83], off nt
	v_lshl_add_u64 v[82:83], s[34:35], 2, v[28:29]
	s_mul_i32 s34, s0, 59
	global_load_dword v81, v[82:83], off nt
	v_lshl_add_u64 v[82:83], s[34:35], 2, v[28:29]
	s_mul_i32 s34, s0, 60
	v_lshl_add_u64 v[84:85], s[34:35], 2, v[28:29]
	s_mul_i32 s34, s0, 61
	global_load_dword v82, v[82:83], off nt
	s_nop 0
	global_load_dword v83, v[84:85], off nt
	v_lshl_add_u64 v[84:85], s[34:35], 2, v[28:29]
	s_mul_i32 s34, s0, 62
	s_mul_i32 s0, s0, 63
	v_lshl_add_u64 v[86:87], s[34:35], 2, v[28:29]
	v_lshl_add_u64 v[28:29], s[0:1], 2, v[28:29]
	global_load_dword v84, v[84:85], off nt
	s_add_u32 s0, s38, s36
	global_load_dword v28, v[28:29], off nt
	s_addc_u32 s34, s39, s37
	global_load_dword v85, v[86:87], off nt
	s_and_b64 s[30:31], s[30:31], exec
	s_cselect_b32 s31, s41, s34
	s_cselect_b32 s30, s40, s0

; #define LAS __attribute__((address_space(3)))
; __device__ __forceinline__ TrItem p0_item_of(const Params& p, int it, int lane) {
;     ...
;     const int nblk = N / 64, kb = r / nblk, nb = r % nblk, k0 = 64 * kb, n0 = 64 * nb;
;     TrItem t; t.src = W + (size_t)k0 * N + srccol(map, n0 + lane); t.N = N; t.K = K; t.fp8 = f8;
;     t.dst = f8 ? (bf16*)((unsigned char*)WT + (size_t)n0 * K + k0) : WT + (size_t)n0 * K + k0; return t;
; }
; __device__ __forceinline__ void tr_range(const Params& p, LAS unsigned char* lds, int first, int stride, int end, int lane, int wave) {
;     LAS float* scr = (LAS float*)(lds + wave * (64 * 65 * 4));
;     if (first >= end) return;
;     float ra[64];
;     TrItem cur = p0_item_of(p, first, lane);
; #pragma unroll
;     for (int i = 0; i < 64; ++i) ra[i] = cur.src[(size_t)i * cur.N];
.LBB0_1532:
	s_lshl_b32 s16, s21, 6
	s_ashr_i32 s17, s16, 31
	s_mul_i32 s11, s17, s0
	s_mul_hi_u32 s18, s16, s0
	s_sub_i32 s1, s97, s46
	s_mul_i32 s10, s96, 0x4100
	s_add_i32 s19, s18, s11
	s_mul_i32 s18, s16, s0
	s_lshl_b32 s78, s1, 3
	s_add_i32 s10, s10, 0
	s_lshl_b64 s[18:19], s[18:19], 2
	s_add_u32 s2, s2, s18
	s_addc_u32 s3, s3, s19
	v_ashrrev_i32_e32 v3, 31, v2
	v_lshl_add_u64 v[2:3], v[2:3], 2, s[2:3]
	s_ashr_i32 s2, s20, 31
	s_mul_hi_u32 s3, s20, s74
	s_mul_i32 s2, s2, s74
	s_add_i32 s3, s3, s2
	s_mul_i32 s2, s20, s74
	s_lshl_b64 s[18:19], s[2:3], 1
	s_add_u32 s11, s4, s18
	s_addc_u32 s20, s5, s19
	s_lshl_b64 s[18:19], s[16:17], 1
	s_add_u32 s11, s11, s18
	s_addc_u32 s18, s20, s19
	s_add_u32 s2, s4, s2
	s_addc_u32 s3, s5, s3
	s_add_u32 s4, s2, s16
	s_addc_u32 s5, s3, s17
	s_mov_b32 s1, 0
	s_and_b64 s[2:3], s[8:9], exec
	s_cselect_b32 s3, s18, s5
	s_cselect_b32 s2, s11, s4
	s_mul_i32 s4, s0, 63
	s_mov_b32 s5, s1
	v_lshl_add_u64 v[4:5], s[4:5], 2, v[2:3]
	s_mul_i32 s4, s0, 62
	global_load_dword v86, v[4:5], off nt
	v_lshl_add_u64 v[4:5], s[4:5], 2, v[2:3]
	s_mul_i32 s4, s0, 61
	global_load_dword v59, v[4:5], off nt
	v_lshl_add_u64 v[4:5], s[4:5], 2, v[2:3]
	s_mul_i32 s4, s0, 60
	global_load_dword v60, v[4:5], off nt
	v_lshl_add_u64 v[4:5], s[4:5], 2, v[2:3]
	s_mul_i32 s4, s0, 59
	global_load_dword v61, v[4:5], off nt
	v_lshl_add_u64 v[4:5], s[4:5], 2, v[2:3]
	s_mul_i32 s4, s0, 58
	global_load_dword v62, v[4:5], off nt
	v_lshl_add_u64 v[4:5], s[4:5], 2, v[2:3]
	s_mul_i32 s4, s0, 57
	global_load_dword v63, v[4:5], off nt
	v_lshl_add_u64 v[4:5], s[4:5], 2, v[2:3]
	s_mul_i32 s4, s0, 56
	global_load_dword v64, v[4:5], off nt
	v_lshl_add_u64 v[4:5], s[4:5], 2, v[2:3]
	s_mul_i32 s4, s0, 55
	global_load_dword v65, v[4:5], off nt
	v_lshl_add_u64 v[4:5], s[4:5], 2, v[2:3]
	s_mul_i32 s4, s0, 54
	global_load_dword v72, v[4:5], off nt
	v_lshl_add_u64 v[4:5], s[4:5], 2, v[2:3]
	s_mul_i32 s4, s0, 53
	global_load_dword v15, v[4:5], off nt
	v_lshl_add_u64 v[4:5], s[4:5], 2, v[2:3]
	s_mul_i32 s4, s0, 52
	global_load_dword v17, v[4:5], off nt
	v_lshl_add_u64 v[4:5], s[4:5], 2, v[2:3]
	s_mul_i32 s4, s0, 51
	global_load_dword v19, v[4:5], off nt
	v_lshl_add_u64 v[4:5], s[4:5], 2, v[2:3]
	s_mul_i32 s4, s0, 50
	global_load_dword v21, v[4:5], off nt
	v_lshl_add_u64 v[4:5], s[4:5], 2, v[2:3]
	s_mul_i32 s4, s0, 49
	global_load_dword v23, v[4:5], off nt
	v_lshl_add_u64 v[4:5], s[4:5], 2, v[2:3]
	s_mul_i32 s4, s0, 48
	global_load_dword v73, v[4:5], off nt
	v_lshl_add_u64 v[4:5], s[4:5], 2, v[2:3]
	s_mul_i32 s4, s0, 47
	global_load_dword v66, v[4:5], off nt
	v_lshl_add_u64 v[4:5], s[4:5], 2, v[2:3]
	s_mul_i32 s4, s0, 46
	global_load_dword v74, v[4:5], off nt
	v_lshl_add_u64 v[4:5], s[4:5], 2, v[2:3]
	s_mul_i32 s4, s0, 45
	global_load_dword v25, v[4:5], off nt
	v_lshl_add_u64 v[4:5], s[4:5], 2, v[2:3]
	s_mul_i32 s4, s0, 44
	global_load_dword v27, v[4:5], off nt
	v_lshl_add_u64 v[4:5], s[4:5], 2, v[2:3]
	s_mul_i32 s4, s0, 43
	global_load_dword v30, v[4:5], off nt
	v_lshl_add_u64 v[4:5], s[4:5], 2, v[2:3]
	s_mul_i32 s4, s0, 42
	global_load_dword v31, v[4:5], off nt
	v_lshl_add_u64 v[4:5], s[4:5], 2, v[2:3]
	s_mul_i32 s4, s0, 41
	global_load_dword v32, v[4:5], off nt
	v_lshl_add_u64 v[4:5], s[4:5], 2, v[2:3]
	s_mul_i32 s4, s0, 40
	global_load_dword v75, v[4:5], off nt
	v_lshl_add_u64 v[4:5], s[4:5], 2, v[2:3]
	s_mul_i32 s4, s0, 39
	global_load_dword v67, v[4:5], off nt
	v_lshl_add_u64 v[4:5], s[4:5], 2, v[2:3]
	s_mul_i32 s4, s0, 38
	global_load_dword v76, v[4:5], off nt
	v_lshl_add_u64 v[4:5], s[4:5], 2, v[2:3]
	s_mul_i32 s4, s0, 37
	global_load_dword v33, v[4:5], off nt
	v_lshl_add_u64 v[4:5], s[4:5], 2, v[2:3]
	s_mul_i32 s4, s0, 36
	global_load_dword v34, v[4:5], off nt
	v_lshl_add_u64 v[4:5], s[4:5], 2, v[2:3]
	s_mul_i32 s4, s0, 35
	global_load_dword v35, v[4:5], off nt
	v_lshl_add_u64 v[4:5], s[4:5], 2, v[2:3]
	s_mul_i32 s4, s0, 34
	global_load_dword v36, v[4:5], off nt
	v_lshl_add_u64 v[4:5], s[4:5], 2, v[2:3]
	s_mul_i32 s4, s0, 33
	global_load_dword v37, v[4:5], off nt
	v_lshl_add_u64 v[4:5], s[4:5], 2, v[2:3]
	s_lshl_b32 s4, s0, 5
	global_load_dword v77, v[4:5], off nt
	v_lshl_add_u64 v[4:5], s[4:5], 2, v[2:3]
	s_mul_i32 s4, s0, 31
	global_load_dword v68, v[4:5], off nt
	v_lshl_add_u64 v[4:5], s[4:5], 2, v[2:3]
	s_mul_i32 s4, s0, 30
	global_load_dword v78, v[4:5], off nt
	v_lshl_add_u64 v[4:5], s[4:5], 2, v[2:3]
	s_mul_i32 s4, s0, 29
	global_load_dword v38, v[4:5], off nt
	v_lshl_add_u64 v[4:5], s[4:5], 2, v[2:3]
	s_mul_i32 s4, s0, 28
	global_load_dword v39, v[4:5], off nt
	v_lshl_add_u64 v[4:5], s[4:5], 2, v[2:3]
	s_mul_i32 s4, s0, 27
	global_load_dword v40, v[4:5], off nt
	v_lshl_add_u64 v[4:5], s[4:5], 2, v[2:3]
	s_mul_i32 s4, s0, 26
	global_load_dword v41, v[4:5], off nt
	v_lshl_add_u64 v[4:5], s[4:5], 2, v[2:3]
	s_mul_i32 s4, s0, 25
	global_load_dword v42, v[4:5], off nt
	v_lshl_add_u64 v[4:5], s[4:5], 2, v[2:3]
	s_mul_i32 s4, s0, 24
	global_load_dword v79, v[4:5], off nt
	v_lshl_add_u64 v[4:5], s[4:5], 2, v[2:3]
	s_mul_i32 s4, s0, 23
	global_load_dword v69, v[4:5], off nt
	v_lshl_add_u64 v[4:5], s[4:5], 2, v[2:3]
	s_mul_i32 s4, s0, 22
	global_load_dword v80, v[4:5], off nt
	v_lshl_add_u64 v[4:5], s[4:5], 2, v[2:3]
	s_mul_i32 s4, s0, 21
	global_load_dword v43, v[4:5], off nt
	v_lshl_add_u64 v[4:5], s[4:5], 2, v[2:3]
	s_mul_i32 s4, s0, 20
	global_load_dword v44, v[4:5], off nt
	v_lshl_add_u64 v[4:5], s[4:5], 2, v[2:3]
; #define LAS __attribute__((address_space(3)))
; #define LDS_WAIT() asm volatile("s_waitcnt lgkmcnt(0)" ::: "memory")
; __device__ __forceinline__ void tr_range(const Params& p, LAS unsigned char* lds, int first, int stride, int end, int lane, int wave) {
;     LAS float* scr = (LAS float*)(lds + wave * (64 * 65 * 4));
;     if (first >= end) return;
;     float ra[64];
;     TrItem cur = p0_item_of(p, first, lane);
; #pragma unroll
;     for (int i = 0; i < 64; ++i) ra[i] = cur.src[(size_t)i * cur.N];
; #pragma unroll 1
;     for (int it = first; it < end; it += stride) {
; #pragma unroll
;         for (int i = 0; i < 64; ++i) scr[i * 65 + lane] = ra[i];
;         const bool more = it + stride < end;
;         TrItem nxt = cur;
;         if (more) { nxt = p0_item_of(p, it + stride, lane);
; #pragma unroll
;             for (int i = 0; i < 64; ++i) ra[i] = nxt.src[(size_t)i * nxt.N]; }
;         LDS_WAIT(); asm volatile("" ::: "memory");
;         if (cur.fp8) {
;             const int c = lane & 3;
; #pragma unroll
;             for (int j = 0; j < 4; ++j) { const int n = (lane >> 2) + 16 * j; const LAS float* s = scr + (16 * c) * 65 + n;
;                 u32x4 o;
;                 o.x = pk4_fp8(s[0 * 65] * W8_SCALE, s[1 * 65] * W8_SCALE, s[2 * 65] * W8_SCALE, s[3 * 65] * W8_SCALE);
;                 o.y = pk4_fp8(s[4 * 65] * W8_SCALE, s[5 * 65] * W8_SCALE, s[6 * 65] * W8_SCALE, s[7 * 65] * W8_SCALE);
;                 o.z = pk4_fp8(s[8 * 65] * W8_SCALE, s[9 * 65] * W8_SCALE, s[10 * 65] * W8_SCALE, s[11 * 65] * W8_SCALE);
;                 o.w = pk4_fp8(s[12 * 65] * W8_SCALE, s[13 * 65] * W8_SCALE, s[14 * 65] * W8_SCALE, s[15 * 65] * W8_SCALE);
;                 *(u32x4*)((unsigned char*)cur.dst + (size_t)n * cur.K + 16 * c) = o; }
;         } else {
;         const int c = lane & 7;
; #pragma unroll
;         for (int j = 0; j < 8; ++j) { const int n = (lane >> 3) + 8 * j; const LAS float* s = scr + (8 * c) * 65 + n;
	s_mul_i32 s4, s0, 19
	global_load_dword v45, v[4:5], off nt
	v_lshl_add_u64 v[4:5], s[4:5], 2, v[2:3]
	s_mul_i32 s4, s0, 18
	global_load_dword v46, v[4:5], off nt
	v_lshl_add_u64 v[4:5], s[4:5], 2, v[2:3]
	s_mul_i32 s4, s0, 17
	global_load_dword v47, v[4:5], off nt
	v_lshl_add_u64 v[4:5], s[4:5], 2, v[2:3]
	s_lshl_b32 s4, s0, 4
	global_load_dword v81, v[4:5], off nt
	v_lshl_add_u64 v[4:5], s[4:5], 2, v[2:3]
	s_mul_i32 s4, s0, 15
	global_load_dword v70, v[4:5], off nt
	v_lshl_add_u64 v[4:5], s[4:5], 2, v[2:3]
	s_mul_i32 s4, s0, 14
	global_load_dword v82, v[4:5], off nt
	v_lshl_add_u64 v[4:5], s[4:5], 2, v[2:3]
	s_mul_i32 s4, s0, 13
	global_load_dword v48, v[4:5], off nt
	v_lshl_add_u64 v[4:5], s[4:5], 2, v[2:3]
	s_mul_i32 s4, s0, 12
	global_load_dword v49, v[4:5], off nt
	v_lshl_add_u64 v[4:5], s[4:5], 2, v[2:3]
	s_mul_i32 s4, s0, 11
	global_load_dword v50, v[4:5], off nt
	v_lshl_add_u64 v[4:5], s[4:5], 2, v[2:3]
	s_mul_i32 s4, s0, 10
	global_load_dword v51, v[4:5], off nt
	v_lshl_add_u64 v[4:5], s[4:5], 2, v[2:3]
	s_mul_i32 s4, s0, 9
	global_load_dword v52, v[4:5], off nt
	v_lshl_add_u64 v[4:5], s[4:5], 2, v[2:3]
	s_lshl_b32 s4, s0, 3
	global_load_dword v83, v[4:5], off nt
	v_lshl_add_u64 v[4:5], s[4:5], 2, v[2:3]
	s_mul_i32 s4, s0, 7
	global_load_dword v71, v[4:5], off nt
	v_lshl_add_u64 v[4:5], s[4:5], 2, v[2:3]
	s_mul_i32 s4, s0, 6
	global_load_dword v84, v[4:5], off nt
	v_lshl_add_u64 v[4:5], s[4:5], 2, v[2:3]
	s_mul_i32 s4, s0, 5
	global_load_dword v53, v[4:5], off nt
	v_lshl_add_u64 v[4:5], s[4:5], 2, v[2:3]
	s_lshl_b32 s4, s0, 2
	global_load_dword v54, v[4:5], off nt
	v_lshl_add_u64 v[4:5], s[4:5], 2, v[2:3]
	s_mul_i32 s4, s0, 3
	global_load_dword v55, v[4:5], off nt
	v_lshl_add_u64 v[4:5], s[4:5], 2, v[2:3]
	s_lshl_b32 s4, s0, 1
	global_load_dword v56, v[4:5], off nt
	v_lshl_add_u64 v[4:5], s[4:5], 2, v[2:3]
	global_load_dword v57, v[4:5], off nt
	v_lshl_add_u64 v[4:5], s[0:1], 2, v[2:3]
	global_load_dword v58, v[4:5], off nt
	global_load_dword v85, v[2:3], off nt
	v_readlane_b32 s16, v253, 32
	v_readlane_b32 s18, v253, 34
	v_readlane_b32 s19, v253, 35
	v_readlane_b32 s17, v253, 33
	s_mov_b64 s[38:39], s[18:19]
	s_mov_b64 s[36:37], s[16:17]
	s_add_u32 s94, s36, 0x8400000
	v_readlane_b32 s20, v253, 36
	v_readlane_b32 s21, v253, 37
	v_readlane_b32 s22, v253, 38
	v_readlane_b32 s23, v253, 39
	v_readlane_b32 s24, v253, 40
	v_readlane_b32 s25, v253, 41
	v_readlane_b32 s26, v253, 42
	v_readlane_b32 s27, v253, 43
	v_readlane_b32 s28, v253, 44
	v_readlane_b32 s29, v253, 45
	v_readlane_b32 s30, v253, 46
	v_readlane_b32 s31, v253, 47
	s_addc_u32 s95, s37, 0
	s_add_u32 s4, s88, 0xf600000
	v_readlane_b32 s16, v253, 10
	s_addc_u32 s5, s89, 0
	v_readlane_b32 s30, v253, 24
	v_readlane_b32 s31, v253, 25
	v_writelane_b32 v252, s4, 14
	v_readlane_b32 s28, v253, 22
	v_readlane_b32 s29, v253, 23
	s_mov_b64 s[50:51], s[30:31]
	v_writelane_b32 v252, s5, 15
	s_add_u32 s4, s50, 0x10800000
	s_addc_u32 s5, s51, 0
	s_add_u32 s76, s88, 0x8800000
	v_writelane_b32 v252, s4, 12
	s_addc_u32 s77, s89, 0
	v_lshlrev_b32_e32 v4, 3, v0
	v_writelane_b32 v252, s5, 13
	s_add_u32 s4, s88, 0x13c00000
	s_addc_u32 s5, s89, 0
	v_lshrrev_b32_e32 v6, 3, v1
	v_and_b32_e32 v4, 56, v4
	s_add_u32 s8, s88, 0x12800000
	v_mul_u32_u24_e32 v8, 0x104, v130
	v_mul_u32_u24_e32 v11, 0x104, v4
	v_and_b32_e32 v9, 60, v1
	v_lshlrev_b32_e32 v13, 2, v6
	s_addc_u32 s9, s89, 0
	v_lshl_add_u32 v3, v1, 2, s10
	v_add3_u32 v9, s10, v8, v9
	v_add3_u32 v11, s10, v11, v13
	s_add_u32 s10, s36, 0x5800000
	s_addc_u32 s11, s37, 0
	v_readlane_b32 s17, v253, 11
	s_add_u32 s16, s88, 0xe000000
	s_addc_u32 s17, s89, 0
	v_writelane_b32 v252, s16, 16
	v_lshrrev_b32_e32 v2, 2, v1
	v_mov_b32_e32 v5, 0
	v_writelane_b32 v252, s17, 17
	s_add_u32 s16, s50, 0xb000000
	s_addc_u32 s17, s51, 0
	v_writelane_b32 v252, s16, 18
	v_and_b32_e32 v7, 31, v0
	v_mov_b32_e32 v131, v5
	v_writelane_b32 v252, s17, 19
	s_add_u32 s16, s36, 0x2c00000
	s_addc_u32 s17, s37, 0
	v_writelane_b32 v252, s16, 22
	v_or_b32_e32 v8, 16, v2
	v_or_b32_e32 v10, 32, v2
	v_writelane_b32 v252, s17, 23
	s_add_u32 s16, s88, 0xca00000
	s_addc_u32 s17, s89, 0
	s_add_u32 s34, s50, 0x5800000
	s_addc_u32 s35, s51, 0
	s_add_u32 s36, s88, 0x3000000
	s_addc_u32 s37, s89, 0
	s_add_u32 s38, s88, 0x12000000
	s_addc_u32 s39, s89, 0
	s_add_u32 s40, s88, 0x10c00000
	s_addc_u32 s41, s89, 0
	s_add_u32 s42, s88, 0xb400000
	s_addc_u32 s43, s89, 0
	s_add_u32 s44, s88, 0x400000
	s_addc_u32 s45, s89, 0
	s_lshl_b32 s0, s97, 3
	s_lshl_b32 s47, s46, 4
	s_sub_i32 s79, s0, s47
	s_lshl_b32 s0, s86, 3
	s_addk_i32 s0, 0xf500
	s_add_i32 s80, s96, s0
	s_lshl_b32 s0, s46, 3
	v_or_b32_e32 v12, 48, v2
	v_or_b32_e32 v14, 8, v6
	v_or_b32_e32 v16, 16, v6
	v_or_b32_e32 v18, 24, v6
	v_or_b32_e32 v20, 32, v6
	v_or_b32_e32 v22, 40, v6
	v_or_b32_e32 v24, 48, v6
	v_or_b32_e32 v26, 56, v6
	v_writelane_b32 v252, s16, 20
	s_sub_i32 s81, 0x7100, s0
	s_mov_b32 s82, 0xc3e00000
	v_lshlrev_b32_e32 v4, 1, v4
	v_mov_b32_e32 v13, 0x43e00000
	s_mov_b32 s88, s75
	s_mov_b64 s[46:47], s[2:3]
	s_mov_b32 s83, s74
	v_readlane_b32 s18, v253, 12
	v_readlane_b32 s19, v253, 13
	v_readlane_b32 s20, v253, 14
	v_readlane_b32 s21, v253, 15
	v_readlane_b32 s22, v253, 16
	v_readlane_b32 s23, v253, 17
	v_readlane_b32 s24, v253, 18
	v_readlane_b32 s25, v253, 19
	v_readlane_b32 s26, v253, 20
	v_readlane_b32 s27, v253, 21
	s_mov_b64 s[48:49], s[28:29]
	v_writelane_b32 v252, s17, 21
	s_branch .LBB0_1535

; __device__ __forceinline__ TrItem p0_item_of(const Params& p, int it, int lane) {
;     ...
;     const int nblk = N / 64, kb = r / nblk, nb = r % nblk, k0 = 64 * kb, n0 = 64 * nb;
;     TrItem t; t.src = W + (size_t)k0 * N + srccol(map, n0 + lane); t.N = N; t.K = K; t.fp8 = f8;
;     t.dst = f8 ? (bf16*)((unsigned char*)WT + (size_t)n0 * K + k0) : WT + (size_t)n0 * K + k0; return t;
; __device__ __forceinline__ void tr_range(const Params& p, LAS unsigned char* lds, int first, int stride, int end, int lane, int wave) {
;     ...
;         const bool more = it + stride < end;
;         TrItem nxt = cur;
;         if (more) { nxt = p0_item_of(p, it + stride, lane);
; #pragma unroll
;             for (int i = 0; i < 64; ++i) ra[i] = nxt.src[(size_t)i * nxt.N]; }
.LBB0_1597:
	s_ashr_i32 s70, s90, 31
	s_lshl_b32 s68, s91, 6
	s_mul_hi_u32 s71, s90, s83
	s_mul_i32 s70, s70, s83
	s_ashr_i32 s69, s68, 31
	s_add_i32 s71, s71, s70
	s_mul_i32 s90, s90, s83
	s_add_u32 s50, s50, s90
	s_addc_u32 s51, s51, s71
	s_add_u32 s72, s50, s90
	s_addc_u32 s73, s51, s71
	s_lshl_b64 s[70:71], s[68:69], 1
	s_add_u32 s70, s72, s70
	s_addc_u32 s71, s73, s71
	s_mul_i32 s72, s69, s0
	s_mul_hi_u32 s73, s68, s0
	s_add_i32 s73, s73, s72
	s_mul_i32 s72, s68, s0
	s_lshl_b64 s[72:73], s[72:73], 2
	s_add_u32 s48, s48, s72
	s_addc_u32 s49, s49, s73
	v_ashrrev_i32_e32 v29, 31, v28
	v_lshl_add_u64 v[28:29], v[28:29], 2, s[48:49]
	v_lshl_add_u64 v[30:31], s[0:1], 2, v[28:29]
	s_lshl_b32 s48, s0, 1
	s_mov_b32 s49, s1
	global_load_dword v85, v[28:29], off nt
	global_load_dword v58, v[30:31], off nt
	v_lshl_add_u64 v[30:31], s[48:49], 2, v[28:29]
	s_mul_i32 s48, s0, 3
	global_load_dword v57, v[30:31], off nt
	v_lshl_add_u64 v[30:31], s[48:49], 2, v[28:29]
	s_lshl_b32 s48, s0, 2
	global_load_dword v56, v[30:31], off nt
	v_lshl_add_u64 v[30:31], s[48:49], 2, v[28:29]
	s_mul_i32 s48, s0, 5
	global_load_dword v55, v[30:31], off nt
	v_lshl_add_u64 v[30:31], s[48:49], 2, v[28:29]
	s_mul_i32 s48, s0, 6
	global_load_dword v54, v[30:31], off nt
	v_lshl_add_u64 v[30:31], s[48:49], 2, v[28:29]
	s_mul_i32 s48, s0, 7
	global_load_dword v53, v[30:31], off nt
	v_lshl_add_u64 v[30:31], s[48:49], 2, v[28:29]
	s_lshl_b32 s48, s0, 3
	global_load_dword v84, v[30:31], off nt
	v_lshl_add_u64 v[30:31], s[48:49], 2, v[28:29]
	s_mul_i32 s48, s0, 9
	global_load_dword v71, v[30:31], off nt
	v_lshl_add_u64 v[30:31], s[48:49], 2, v[28:29]
	s_mul_i32 s48, s0, 10
	global_load_dword v83, v[30:31], off nt
	v_lshl_add_u64 v[30:31], s[48:49], 2, v[28:29]
	s_mul_i32 s48, s0, 11
	global_load_dword v52, v[30:31], off nt
	v_lshl_add_u64 v[30:31], s[48:49], 2, v[28:29]
	s_mul_i32 s48, s0, 12
	global_load_dword v51, v[30:31], off nt
	v_lshl_add_u64 v[30:31], s[48:49], 2, v[28:29]
	s_mul_i32 s48, s0, 13
	global_load_dword v50, v[30:31], off nt
	v_lshl_add_u64 v[30:31], s[48:49], 2, v[28:29]
	s_mul_i32 s48, s0, 14
	global_load_dword v49, v[30:31], off nt
	v_lshl_add_u64 v[30:31], s[48:49], 2, v[28:29]
	s_mul_i32 s48, s0, 15
	global_load_dword v48, v[30:31], off nt
	v_lshl_add_u64 v[30:31], s[48:49], 2, v[28:29]
	s_lshl_b32 s48, s0, 4
	global_load_dword v82, v[30:31], off nt
	v_lshl_add_u64 v[30:31], s[48:49], 2, v[28:29]
	s_mul_i32 s48, s0, 17
	global_load_dword v70, v[30:31], off nt
	v_lshl_add_u64 v[30:31], s[48:49], 2, v[28:29]
	s_mul_i32 s48, s0, 18
	global_load_dword v81, v[30:31], off nt
	v_lshl_add_u64 v[30:31], s[48:49], 2, v[28:29]
	s_mul_i32 s48, s0, 19
	global_load_dword v47, v[30:31], off nt
	v_lshl_add_u64 v[30:31], s[48:49], 2, v[28:29]
	s_mul_i32 s48, s0, 20
	global_load_dword v46, v[30:31], off nt
	v_lshl_add_u64 v[30:31], s[48:49], 2, v[28:29]
	s_mul_i32 s48, s0, 21
	global_load_dword v45, v[30:31], off nt
	v_lshl_add_u64 v[30:31], s[48:49], 2, v[28:29]
	s_mul_i32 s48, s0, 22
	global_load_dword v44, v[30:31], off nt
	v_lshl_add_u64 v[30:31], s[48:49], 2, v[28:29]
	s_mul_i32 s48, s0, 23
	global_load_dword v43, v[30:31], off nt
	v_lshl_add_u64 v[30:31], s[48:49], 2, v[28:29]
	s_mul_i32 s48, s0, 24
	global_load_dword v80, v[30:31], off nt
	v_lshl_add_u64 v[30:31], s[48:49], 2, v[28:29]
	s_mul_i32 s48, s0, 25
	global_load_dword v69, v[30:31], off nt
	v_lshl_add_u64 v[30:31], s[48:49], 2, v[28:29]
	s_mul_i32 s48, s0, 26
	global_load_dword v79, v[30:31], off nt
	v_lshl_add_u64 v[30:31], s[48:49], 2, v[28:29]
	s_mul_i32 s48, s0, 27
	global_load_dword v42, v[30:31], off nt
	v_lshl_add_u64 v[30:31], s[48:49], 2, v[28:29]
	s_mul_i32 s48, s0, 28
	global_load_dword v41, v[30:31], off nt
	v_lshl_add_u64 v[30:31], s[48:49], 2, v[28:29]
	s_mul_i32 s48, s0, 29
	global_load_dword v40, v[30:31], off nt
	v_lshl_add_u64 v[30:31], s[48:49], 2, v[28:29]
	s_mul_i32 s48, s0, 30
	global_load_dword v39, v[30:31], off nt
; __device__ __forceinline__ TrItem p0_item_of(const Params& p, int it, int lane) {
;     ...
;     t.dst = f8 ? (bf16*)((unsigned char*)WT + (size_t)n0 * K + k0) : WT + (size_t)n0 * K + k0; return t;
; __device__ __forceinline__ void tr_range(const Params& p, LAS unsigned char* lds, int first, int stride, int end, int lane, int wave) {
;     ...
;         if (more) { nxt = p0_item_of(p, it + stride, lane);
; #pragma unroll
;             for (int i = 0; i < 64; ++i) ra[i] = nxt.src[(size_t)i * nxt.N]; }
	v_lshl_add_u64 v[30:31], s[48:49], 2, v[28:29]
	s_mul_i32 s48, s0, 31
	global_load_dword v38, v[30:31], off nt
	v_lshl_add_u64 v[30:31], s[48:49], 2, v[28:29]
	s_lshl_b32 s48, s0, 5
	global_load_dword v78, v[30:31], off nt
	v_lshl_add_u64 v[30:31], s[48:49], 2, v[28:29]
	s_mul_i32 s48, s0, 33
	global_load_dword v68, v[30:31], off nt
	v_lshl_add_u64 v[30:31], s[48:49], 2, v[28:29]
	s_mul_i32 s48, s0, 34
	global_load_dword v77, v[30:31], off nt
	v_lshl_add_u64 v[30:31], s[48:49], 2, v[28:29]
	s_mul_i32 s48, s0, 35
	global_load_dword v37, v[30:31], off nt
	v_lshl_add_u64 v[30:31], s[48:49], 2, v[28:29]
	s_mul_i32 s48, s0, 36
	global_load_dword v36, v[30:31], off nt
	v_lshl_add_u64 v[30:31], s[48:49], 2, v[28:29]
	s_mul_i32 s48, s0, 37
	global_load_dword v35, v[30:31], off nt
	v_lshl_add_u64 v[30:31], s[48:49], 2, v[28:29]
	s_mul_i32 s48, s0, 38
	global_load_dword v34, v[30:31], off nt
	v_lshl_add_u64 v[30:31], s[48:49], 2, v[28:29]
	s_mul_i32 s48, s0, 39
	global_load_dword v33, v[30:31], off nt
	v_lshl_add_u64 v[30:31], s[48:49], 2, v[28:29]
	s_mul_i32 s48, s0, 40
	global_load_dword v76, v[30:31], off nt
	v_lshl_add_u64 v[30:31], s[48:49], 2, v[28:29]
	s_mul_i32 s48, s0, 41
	global_load_dword v67, v[30:31], off nt
	v_lshl_add_u64 v[30:31], s[48:49], 2, v[28:29]
	s_mul_i32 s48, s0, 42
	global_load_dword v75, v[30:31], off nt
	v_lshl_add_u64 v[30:31], s[48:49], 2, v[28:29]
	s_mul_i32 s48, s0, 43
	global_load_dword v32, v[30:31], off nt
	v_lshl_add_u64 v[30:31], s[48:49], 2, v[28:29]
	s_mul_i32 s48, s0, 44
	v_lshl_add_u64 v[60:61], s[48:49], 2, v[28:29]
	s_mul_i32 s48, s0, 45
	global_load_dword v31, v[30:31], off nt
	s_nop 0
	global_load_dword v30, v[60:61], off nt
	v_lshl_add_u64 v[60:61], s[48:49], 2, v[28:29]
	s_mul_i32 s48, s0, 46
	global_load_dword v27, v[60:61], off nt
	v_lshl_add_u64 v[60:61], s[48:49], 2, v[28:29]
	s_mul_i32 s48, s0, 47
	global_load_dword v25, v[60:61], off nt
	v_lshl_add_u64 v[60:61], s[48:49], 2, v[28:29]
	s_mul_i32 s48, s0, 48
	global_load_dword v74, v[60:61], off nt
	v_lshl_add_u64 v[60:61], s[48:49], 2, v[28:29]
	s_mul_i32 s48, s0, 49
	global_load_dword v66, v[60:61], off nt
	v_lshl_add_u64 v[60:61], s[48:49], 2, v[28:29]
	s_mul_i32 s48, s0, 50
	global_load_dword v73, v[60:61], off nt
	v_lshl_add_u64 v[60:61], s[48:49], 2, v[28:29]
	s_mul_i32 s48, s0, 51
	global_load_dword v23, v[60:61], off nt
	v_lshl_add_u64 v[60:61], s[48:49], 2, v[28:29]
	s_mul_i32 s48, s0, 52
	global_load_dword v21, v[60:61], off nt
	v_lshl_add_u64 v[60:61], s[48:49], 2, v[28:29]
	s_mul_i32 s48, s0, 53
	global_load_dword v19, v[60:61], off nt
	v_lshl_add_u64 v[60:61], s[48:49], 2, v[28:29]
	s_mul_i32 s48, s0, 54
	global_load_dword v17, v[60:61], off nt
	v_lshl_add_u64 v[60:61], s[48:49], 2, v[28:29]
	s_mul_i32 s48, s0, 55
	global_load_dword v15, v[60:61], off nt
	v_lshl_add_u64 v[60:61], s[48:49], 2, v[28:29]
	s_mul_i32 s48, s0, 56
	global_load_dword v72, v[60:61], off nt
	v_lshl_add_u64 v[60:61], s[48:49], 2, v[28:29]
	s_mul_i32 s48, s0, 57
	global_load_dword v65, v[60:61], off nt
	v_lshl_add_u64 v[60:61], s[48:49], 2, v[28:29]
	s_mul_i32 s48, s0, 58
	global_load_dword v64, v[60:61], off nt
	v_lshl_add_u64 v[60:61], s[48:49], 2, v[28:29]
	s_mul_i32 s48, s0, 59
	global_load_dword v63, v[60:61], off nt
	v_lshl_add_u64 v[60:61], s[48:49], 2, v[28:29]
	s_mul_i32 s48, s0, 60
	global_load_dword v62, v[60:61], off nt
	v_lshl_add_u64 v[60:61], s[48:49], 2, v[28:29]
	s_mul_i32 s48, s0, 61
	v_lshl_add_u64 v[86:87], s[48:49], 2, v[28:29]
	s_mul_i32 s48, s0, 62
	s_mul_i32 s0, s0, 63
	global_load_dword v61, v[60:61], off nt
	s_nop 0
	global_load_dword v60, v[86:87], off nt
	v_lshl_add_u64 v[86:87], s[48:49], 2, v[28:29]
	v_lshl_add_u64 v[28:29], s[0:1], 2, v[28:29]
	global_load_dword v59, v[86:87], off nt
	s_add_u32 s0, s50, s68
	global_load_dword v86, v[28:29], off nt
	s_addc_u32 s48, s51, s69
	s_and_b64 s[46:47], s[46:47], exec
	s_cselect_b32 s47, s71, s48
	s_cselect_b32 s46, s70, s0

; #define LAS __attribute__((address_space(3)))
; __device__ __forceinline__ TrItem p0_item_of(const Params& p, int it, int lane) {
;     ...
;     const int nblk = N / 64, kb = r / nblk, nb = r % nblk, k0 = 64 * kb, n0 = 64 * nb;
;     TrItem t; t.src = W + (size_t)k0 * N + srccol(map, n0 + lane); t.N = N; t.K = K; t.fp8 = f8;
;     t.dst = f8 ? (bf16*)((unsigned char*)WT + (size_t)n0 * K + k0) : WT + (size_t)n0 * K + k0; return t;
; }
; __device__ __forceinline__ void tr_range(const Params& p, LAS unsigned char* lds, int first, int stride, int end, int lane, int wave) {
;     LAS float* scr = (LAS float*)(lds + wave * (64 * 65 * 4));
;     if (first >= end) return;
;     float ra[64];
;     TrItem cur = p0_item_of(p, first, lane);
; #pragma unroll
;     for (int i = 0; i < 64; ++i) ra[i] = cur.src[(size_t)i * cur.N];
.LBB0_2008:
	s_lshl_b32 s10, s19, 6
	s_ashr_i32 s11, s10, 31
	s_mul_i32 s9, s11, s0
	s_mul_hi_u32 s16, s10, s0
	s_sub_i32 s1, s97, s44
	s_mul_i32 s8, s96, 0x4100
	s_add_i32 s17, s16, s9
	s_mul_i32 s16, s10, s0
	s_lshl_b32 s70, s1, 3
	s_add_i32 s8, s8, 0
	s_lshl_b64 s[16:17], s[16:17], 2
	s_add_u32 s2, s2, s16
	s_addc_u32 s3, s3, s17
	v_ashrrev_i32_e32 v3, 31, v2
	v_lshl_add_u64 v[2:3], v[2:3], 2, s[2:3]
	s_ashr_i32 s2, s18, 31
	s_mul_hi_u32 s3, s18, s68
	s_mul_i32 s2, s2, s68
	s_add_i32 s3, s3, s2
	s_mul_i32 s2, s18, s68
	s_lshl_b64 s[16:17], s[2:3], 1
	s_add_u32 s9, s4, s16
	s_addc_u32 s18, s5, s17
	s_lshl_b64 s[16:17], s[10:11], 1
	s_add_u32 s9, s9, s16
	s_addc_u32 s16, s18, s17
	s_add_u32 s2, s4, s2
	s_addc_u32 s3, s5, s3
	s_add_u32 s4, s2, s10
	s_addc_u32 s5, s3, s11
	s_mov_b32 s1, 0
	s_and_b64 s[2:3], s[6:7], exec
	s_cselect_b32 s3, s16, s5
	s_cselect_b32 s2, s9, s4
	s_mul_i32 s4, s0, 63
	s_mov_b32 s5, s1
	v_lshl_add_u64 v[4:5], s[4:5], 2, v[2:3]
	s_mul_i32 s4, s0, 62
	global_load_dword v86, v[4:5], off nt
	v_lshl_add_u64 v[4:5], s[4:5], 2, v[2:3]
	s_mul_i32 s4, s0, 61
	global_load_dword v59, v[4:5], off nt
	v_lshl_add_u64 v[4:5], s[4:5], 2, v[2:3]
	s_mul_i32 s4, s0, 60
	global_load_dword v60, v[4:5], off nt
	v_lshl_add_u64 v[4:5], s[4:5], 2, v[2:3]
	s_mul_i32 s4, s0, 59
	global_load_dword v61, v[4:5], off nt
	v_lshl_add_u64 v[4:5], s[4:5], 2, v[2:3]
	s_mul_i32 s4, s0, 58
	global_load_dword v62, v[4:5], off nt
	v_lshl_add_u64 v[4:5], s[4:5], 2, v[2:3]
	s_mul_i32 s4, s0, 57
	global_load_dword v63, v[4:5], off nt
	v_lshl_add_u64 v[4:5], s[4:5], 2, v[2:3]
	s_mul_i32 s4, s0, 56
	global_load_dword v64, v[4:5], off nt
	v_lshl_add_u64 v[4:5], s[4:5], 2, v[2:3]
	s_mul_i32 s4, s0, 55
	global_load_dword v65, v[4:5], off nt
	v_lshl_add_u64 v[4:5], s[4:5], 2, v[2:3]
	s_mul_i32 s4, s0, 54
	global_load_dword v72, v[4:5], off nt
	v_lshl_add_u64 v[4:5], s[4:5], 2, v[2:3]
	s_mul_i32 s4, s0, 53
	global_load_dword v15, v[4:5], off nt
	v_lshl_add_u64 v[4:5], s[4:5], 2, v[2:3]
	s_mul_i32 s4, s0, 52
	global_load_dword v17, v[4:5], off nt
	v_lshl_add_u64 v[4:5], s[4:5], 2, v[2:3]
	s_mul_i32 s4, s0, 51
	global_load_dword v19, v[4:5], off nt
	v_lshl_add_u64 v[4:5], s[4:5], 2, v[2:3]
	s_mul_i32 s4, s0, 50
	global_load_dword v21, v[4:5], off nt
	v_lshl_add_u64 v[4:5], s[4:5], 2, v[2:3]
	s_mul_i32 s4, s0, 49
	global_load_dword v23, v[4:5], off nt
	v_lshl_add_u64 v[4:5], s[4:5], 2, v[2:3]
	s_mul_i32 s4, s0, 48
	global_load_dword v73, v[4:5], off nt
	v_lshl_add_u64 v[4:5], s[4:5], 2, v[2:3]
	s_mul_i32 s4, s0, 47
	global_load_dword v66, v[4:5], off nt
	v_lshl_add_u64 v[4:5], s[4:5], 2, v[2:3]
	s_mul_i32 s4, s0, 46
	global_load_dword v74, v[4:5], off nt
	v_lshl_add_u64 v[4:5], s[4:5], 2, v[2:3]
	s_mul_i32 s4, s0, 45
	global_load_dword v25, v[4:5], off nt
	v_lshl_add_u64 v[4:5], s[4:5], 2, v[2:3]
	s_mul_i32 s4, s0, 44
	global_load_dword v27, v[4:5], off nt
	v_lshl_add_u64 v[4:5], s[4:5], 2, v[2:3]
	s_mul_i32 s4, s0, 43
	global_load_dword v30, v[4:5], off nt
	v_lshl_add_u64 v[4:5], s[4:5], 2, v[2:3]
	s_mul_i32 s4, s0, 42
	global_load_dword v31, v[4:5], off nt
	v_lshl_add_u64 v[4:5], s[4:5], 2, v[2:3]
	s_mul_i32 s4, s0, 41
	global_load_dword v32, v[4:5], off nt
	v_lshl_add_u64 v[4:5], s[4:5], 2, v[2:3]
	s_mul_i32 s4, s0, 40
	global_load_dword v75, v[4:5], off nt
	v_lshl_add_u64 v[4:5], s[4:5], 2, v[2:3]
	s_mul_i32 s4, s0, 39
	global_load_dword v67, v[4:5], off nt
	v_lshl_add_u64 v[4:5], s[4:5], 2, v[2:3]
	s_mul_i32 s4, s0, 38
	global_load_dword v76, v[4:5], off nt
	v_lshl_add_u64 v[4:5], s[4:5], 2, v[2:3]
	s_mul_i32 s4, s0, 37
	global_load_dword v33, v[4:5], off nt
	v_lshl_add_u64 v[4:5], s[4:5], 2, v[2:3]
	s_mul_i32 s4, s0, 36
	global_load_dword v34, v[4:5], off nt
	v_lshl_add_u64 v[4:5], s[4:5], 2, v[2:3]
	s_mul_i32 s4, s0, 35
	global_load_dword v35, v[4:5], off nt
	v_lshl_add_u64 v[4:5], s[4:5], 2, v[2:3]
	s_mul_i32 s4, s0, 34
	global_load_dword v36, v[4:5], off nt
	v_lshl_add_u64 v[4:5], s[4:5], 2, v[2:3]
	s_mul_i32 s4, s0, 33
	global_load_dword v37, v[4:5], off nt
	v_lshl_add_u64 v[4:5], s[4:5], 2, v[2:3]
	s_lshl_b32 s4, s0, 5
	global_load_dword v77, v[4:5], off nt
	v_lshl_add_u64 v[4:5], s[4:5], 2, v[2:3]
	s_mul_i32 s4, s0, 31
	global_load_dword v68, v[4:5], off nt
	v_lshl_add_u64 v[4:5], s[4:5], 2, v[2:3]
	s_mul_i32 s4, s0, 30
	global_load_dword v78, v[4:5], off nt
	v_lshl_add_u64 v[4:5], s[4:5], 2, v[2:3]
	s_mul_i32 s4, s0, 29
	global_load_dword v38, v[4:5], off nt
	v_lshl_add_u64 v[4:5], s[4:5], 2, v[2:3]
	s_mul_i32 s4, s0, 28
	global_load_dword v39, v[4:5], off nt
	v_lshl_add_u64 v[4:5], s[4:5], 2, v[2:3]
	s_mul_i32 s4, s0, 27
	global_load_dword v40, v[4:5], off nt
	v_lshl_add_u64 v[4:5], s[4:5], 2, v[2:3]
	s_mul_i32 s4, s0, 26
	global_load_dword v41, v[4:5], off nt
	v_lshl_add_u64 v[4:5], s[4:5], 2, v[2:3]
	s_mul_i32 s4, s0, 25
	global_load_dword v42, v[4:5], off nt
	v_lshl_add_u64 v[4:5], s[4:5], 2, v[2:3]
	s_mul_i32 s4, s0, 24
	global_load_dword v79, v[4:5], off nt
	v_lshl_add_u64 v[4:5], s[4:5], 2, v[2:3]
	s_mul_i32 s4, s0, 23
	global_load_dword v69, v[4:5], off nt
	v_lshl_add_u64 v[4:5], s[4:5], 2, v[2:3]
	s_mul_i32 s4, s0, 22
	global_load_dword v80, v[4:5], off nt
	v_lshl_add_u64 v[4:5], s[4:5], 2, v[2:3]
	s_mul_i32 s4, s0, 21
	global_load_dword v43, v[4:5], off nt
	v_lshl_add_u64 v[4:5], s[4:5], 2, v[2:3]
	s_mul_i32 s4, s0, 20
	global_load_dword v44, v[4:5], off nt
	v_lshl_add_u64 v[4:5], s[4:5], 2, v[2:3]
; #define LAS __attribute__((address_space(3)))
; #define LDS_WAIT() asm volatile("s_waitcnt lgkmcnt(0)" ::: "memory")
; __device__ __forceinline__ void tr_range(const Params& p, LAS unsigned char* lds, int first, int stride, int end, int lane, int wave) {
;     LAS float* scr = (LAS float*)(lds + wave * (64 * 65 * 4));
;     if (first >= end) return;
;     float ra[64];
;     TrItem cur = p0_item_of(p, first, lane);
; #pragma unroll
;     for (int i = 0; i < 64; ++i) ra[i] = cur.src[(size_t)i * cur.N];
; #pragma unroll 1
;     for (int it = first; it < end; it += stride) {
; #pragma unroll
;         for (int i = 0; i < 64; ++i) scr[i * 65 + lane] = ra[i];
;         const bool more = it + stride < end;
;         TrItem nxt = cur;
;         if (more) { nxt = p0_item_of(p, it + stride, lane);
; #pragma unroll
;             for (int i = 0; i < 64; ++i) ra[i] = nxt.src[(size_t)i * nxt.N]; }
;         LDS_WAIT(); asm volatile("" ::: "memory");
;         if (cur.fp8) {
;             const int c = lane & 3;
; #pragma unroll
;             for (int j = 0; j < 4; ++j) { const int n = (lane >> 2) + 16 * j; const LAS float* s = scr + (16 * c) * 65 + n;
;                 u32x4 o;
;                 o.x = pk4_fp8(s[0 * 65] * W8_SCALE, s[1 * 65] * W8_SCALE, s[2 * 65] * W8_SCALE, s[3 * 65] * W8_SCALE);
;                 o.y = pk4_fp8(s[4 * 65] * W8_SCALE, s[5 * 65] * W8_SCALE, s[6 * 65] * W8_SCALE, s[7 * 65] * W8_SCALE);
;                 o.z = pk4_fp8(s[8 * 65] * W8_SCALE, s[9 * 65] * W8_SCALE, s[10 * 65] * W8_SCALE, s[11 * 65] * W8_SCALE);
;                 o.w = pk4_fp8(s[12 * 65] * W8_SCALE, s[13 * 65] * W8_SCALE, s[14 * 65] * W8_SCALE, s[15 * 65] * W8_SCALE);
;                 *(u32x4*)((unsigned char*)cur.dst + (size_t)n * cur.K + 16 * c) = o; }
;         } else {
;         const int c = lane & 7;
; #pragma unroll
;         for (int j = 0; j < 8; ++j) { const int n = (lane >> 3) + 8 * j; const LAS float* s = scr + (8 * c) * 65 + n;
	s_mul_i32 s4, s0, 19
	global_load_dword v45, v[4:5], off nt
	v_lshl_add_u64 v[4:5], s[4:5], 2, v[2:3]
	s_mul_i32 s4, s0, 18
	global_load_dword v46, v[4:5], off nt
	v_lshl_add_u64 v[4:5], s[4:5], 2, v[2:3]
	s_mul_i32 s4, s0, 17
	global_load_dword v47, v[4:5], off nt
	v_lshl_add_u64 v[4:5], s[4:5], 2, v[2:3]
	s_lshl_b32 s4, s0, 4
	global_load_dword v81, v[4:5], off nt
	v_lshl_add_u64 v[4:5], s[4:5], 2, v[2:3]
	s_mul_i32 s4, s0, 15
	global_load_dword v70, v[4:5], off nt
	v_lshl_add_u64 v[4:5], s[4:5], 2, v[2:3]
	s_mul_i32 s4, s0, 14
	global_load_dword v82, v[4:5], off nt
	v_lshl_add_u64 v[4:5], s[4:5], 2, v[2:3]
	s_mul_i32 s4, s0, 13
	global_load_dword v48, v[4:5], off nt
	v_lshl_add_u64 v[4:5], s[4:5], 2, v[2:3]
	s_mul_i32 s4, s0, 12
	global_load_dword v49, v[4:5], off nt
	v_lshl_add_u64 v[4:5], s[4:5], 2, v[2:3]
	s_mul_i32 s4, s0, 11
	global_load_dword v50, v[4:5], off nt
	v_lshl_add_u64 v[4:5], s[4:5], 2, v[2:3]
	s_mul_i32 s4, s0, 10
	global_load_dword v51, v[4:5], off nt
	v_lshl_add_u64 v[4:5], s[4:5], 2, v[2:3]
	s_mul_i32 s4, s0, 9
	global_load_dword v52, v[4:5], off nt
	v_lshl_add_u64 v[4:5], s[4:5], 2, v[2:3]
	s_lshl_b32 s4, s0, 3
	global_load_dword v83, v[4:5], off nt
	v_lshl_add_u64 v[4:5], s[4:5], 2, v[2:3]
	s_mul_i32 s4, s0, 7
	global_load_dword v71, v[4:5], off nt
	v_lshl_add_u64 v[4:5], s[4:5], 2, v[2:3]
	s_mul_i32 s4, s0, 6
	global_load_dword v84, v[4:5], off nt
	v_lshl_add_u64 v[4:5], s[4:5], 2, v[2:3]
	s_mul_i32 s4, s0, 5
	global_load_dword v53, v[4:5], off nt
	v_lshl_add_u64 v[4:5], s[4:5], 2, v[2:3]
	s_lshl_b32 s4, s0, 2
	global_load_dword v54, v[4:5], off nt
	v_lshl_add_u64 v[4:5], s[4:5], 2, v[2:3]
	s_mul_i32 s4, s0, 3
	global_load_dword v55, v[4:5], off nt
	v_lshl_add_u64 v[4:5], s[4:5], 2, v[2:3]
	s_lshl_b32 s4, s0, 1
	global_load_dword v56, v[4:5], off nt
	v_lshl_add_u64 v[4:5], s[4:5], 2, v[2:3]
	global_load_dword v57, v[4:5], off nt
	v_lshl_add_u64 v[4:5], s[0:1], 2, v[2:3]
	global_load_dword v58, v[4:5], off nt
	global_load_dword v85, v[2:3], off nt
	v_readlane_b32 s16, v253, 32
	v_readlane_b32 s18, v253, 34
	v_readlane_b32 s19, v253, 35
	v_readlane_b32 s17, v253, 33
	s_mov_b64 s[38:39], s[18:19]
	s_mov_b64 s[36:37], s[16:17]
	s_add_u32 s4, s36, 0x8400000
	s_addc_u32 s5, s37, 0
	v_writelane_b32 v252, s4, 22
	v_readlane_b32 s20, v253, 36
	v_readlane_b32 s21, v253, 37
	v_readlane_b32 s22, v253, 38
	v_readlane_b32 s23, v253, 39
	v_readlane_b32 s24, v253, 40
	v_readlane_b32 s25, v253, 41
	v_readlane_b32 s26, v253, 42
	v_readlane_b32 s27, v253, 43
	v_readlane_b32 s28, v253, 44
	v_readlane_b32 s29, v253, 45
	v_readlane_b32 s30, v253, 46
	v_readlane_b32 s31, v253, 47
	v_writelane_b32 v252, s5, 23
	s_add_u32 s4, s88, 0xf600000
	s_addc_u32 s5, s89, 0
	v_readlane_b32 s16, v253, 10
	v_writelane_b32 v252, s4, 20
	v_readlane_b32 s30, v253, 24
	v_readlane_b32 s31, v253, 25
	v_writelane_b32 v252, s5, 21
	s_add_u32 s4, s30, 0x10800000
	s_addc_u32 s5, s31, 0
	v_writelane_b32 v252, s4, 18
	s_mov_b32 s14, s76
	v_lshlrev_b32_e32 v4, 3, v0
	v_writelane_b32 v252, s5, 19
	s_add_u32 s4, s88, 0x8800000
	s_addc_u32 s5, s89, 0
	s_add_u32 s76, s88, 0x13c00000
	s_addc_u32 s77, s89, 0
	s_add_u32 s12, s36, 0x5800000
	v_writelane_b32 v252, s4, 16
	s_addc_u32 s13, s37, 0
	v_lshrrev_b32_e32 v6, 3, v1
	v_writelane_b32 v252, s5, 17
	s_add_u32 s4, s88, 0xe000000
	s_addc_u32 s5, s89, 0
	v_and_b32_e32 v4, 56, v4
	s_add_u32 s6, s30, 0xb000000
	v_mul_u32_u24_e32 v8, 0x104, v146
	v_mul_u32_u24_e32 v11, 0x104, v4
	v_and_b32_e32 v9, 60, v1
	v_lshlrev_b32_e32 v13, 2, v6
	s_addc_u32 s7, s31, 0
	v_lshl_add_u32 v3, v1, 2, s8
	v_add3_u32 v9, s8, v8, v9
	v_add3_u32 v11, s8, v11, v13
	s_add_u32 s8, s88, 0x5c00000
	s_addc_u32 s9, s89, 0
	s_add_u32 s10, s36, 0x2c00000
	s_addc_u32 s11, s37, 0
	v_readlane_b32 s17, v253, 11
	s_add_u32 s16, s88, 0xca00000
	s_addc_u32 s17, s89, 0
	v_readlane_b32 s18, v253, 12
	v_readlane_b32 s19, v253, 13
	v_readlane_b32 s20, v253, 14
	v_readlane_b32 s21, v253, 15
	v_readlane_b32 s22, v253, 16
	v_readlane_b32 s23, v253, 17
	v_readlane_b32 s24, v253, 18
	v_readlane_b32 s25, v253, 19
	v_readlane_b32 s26, v253, 20
	v_readlane_b32 s27, v253, 21
	v_readlane_b32 s28, v253, 22
	v_readlane_b32 s29, v253, 23
	v_writelane_b32 v253, s16, 56
	v_lshrrev_b32_e32 v2, 2, v1
	v_mov_b32_e32 v5, 0
	v_writelane_b32 v253, s17, 57
	s_add_u32 s16, s30, 0x5800000
	s_addc_u32 s17, s31, 0
	s_add_u32 s34, s88, 0x3000000
	s_addc_u32 s35, s89, 0
	s_add_u32 s36, s88, 0x12000000
	s_addc_u32 s37, s89, 0
	s_add_u32 s38, s88, 0x10c00000
	s_addc_u32 s39, s89, 0
	s_add_u32 s40, s88, 0xb400000
	s_addc_u32 s41, s89, 0
	s_add_u32 s42, s88, 0x400000
	s_addc_u32 s43, s89, 0
	s_lshl_b32 s0, s97, 3
	s_lshl_b32 s45, s44, 4
	s_sub_i32 s71, s0, s45
	s_lshl_b32 s0, s86, 3
	s_addk_i32 s0, 0xe600
	v_writelane_b32 v253, s16, 54
	s_add_i32 s72, s96, s0
	s_lshl_b32 s0, s44, 3
	v_and_b32_e32 v7, 31, v0
	v_mov_b32_e32 v147, v5
	v_or_b32_e32 v8, 16, v2
	v_or_b32_e32 v10, 32, v2
	v_or_b32_e32 v12, 48, v2
	v_or_b32_e32 v14, 8, v6
	v_or_b32_e32 v16, 16, v6
	v_or_b32_e32 v18, 24, v6
	v_or_b32_e32 v20, 32, v6
	v_or_b32_e32 v22, 40, v6
	v_or_b32_e32 v24, 48, v6
	v_or_b32_e32 v26, 56, v6
	v_writelane_b32 v253, s17, 55
	s_sub_i32 s73, 0x9d00, s0
	s_mov_b32 s74, 0xc3e00000
	v_lshlrev_b32_e32 v4, 1, v4
	v_mov_b32_e32 v13, 0x43e00000
	s_mov_b32 s78, s69
	s_mov_b64 s[44:45], s[2:3]
	s_mov_b32 s75, s68
	s_branch .LBB0_2011

; __device__ __forceinline__ TrItem p0_item_of(const Params& p, int it, int lane) {
;     ...
;     const int nblk = N / 64, kb = r / nblk, nb = r % nblk, k0 = 64 * kb, n0 = 64 * nb;
;     TrItem t; t.src = W + (size_t)k0 * N + srccol(map, n0 + lane); t.N = N; t.K = K; t.fp8 = f8;
;     t.dst = f8 ? (bf16*)((unsigned char*)WT + (size_t)n0 * K + k0) : WT + (size_t)n0 * K + k0; return t;
; __device__ __forceinline__ void tr_range(const Params& p, LAS unsigned char* lds, int first, int stride, int end, int lane, int wave) {
;     ...
;         const bool more = it + stride < end;
;         TrItem nxt = cur;
;         if (more) { nxt = p0_item_of(p, it + stride, lane);
; #pragma unroll
;             for (int i = 0; i < 64; ++i) ra[i] = nxt.src[(size_t)i * nxt.N]; }
.LBB0_2073:
	s_ashr_i32 s56, s80, 31
	s_lshl_b32 s50, s81, 6
	s_mul_hi_u32 s57, s80, s75
	s_mul_i32 s56, s56, s75
	s_ashr_i32 s51, s50, 31
	s_add_i32 s57, s57, s56
	s_mul_i32 s80, s80, s75
	s_add_u32 s48, s48, s80
	s_addc_u32 s49, s49, s57
	s_add_u32 s58, s48, s80
	s_addc_u32 s59, s49, s57
	s_lshl_b64 s[56:57], s[50:51], 1
	s_add_u32 s56, s58, s56
	s_addc_u32 s57, s59, s57
	s_mul_i32 s58, s51, s0
	s_mul_hi_u32 s59, s50, s0
	s_add_i32 s59, s59, s58
	s_mul_i32 s58, s50, s0
	s_lshl_b64 s[58:59], s[58:59], 2
	s_add_u32 s46, s46, s58
	s_addc_u32 s47, s47, s59
	v_ashrrev_i32_e32 v29, 31, v28
	v_lshl_add_u64 v[28:29], v[28:29], 2, s[46:47]
	v_lshl_add_u64 v[30:31], s[0:1], 2, v[28:29]
	s_lshl_b32 s46, s0, 1
	s_mov_b32 s47, s1
	global_load_dword v85, v[28:29], off nt
	global_load_dword v58, v[30:31], off nt
	v_lshl_add_u64 v[30:31], s[46:47], 2, v[28:29]
	s_mul_i32 s46, s0, 3
	global_load_dword v57, v[30:31], off nt
	v_lshl_add_u64 v[30:31], s[46:47], 2, v[28:29]
	s_lshl_b32 s46, s0, 2
	global_load_dword v56, v[30:31], off nt
	v_lshl_add_u64 v[30:31], s[46:47], 2, v[28:29]
	s_mul_i32 s46, s0, 5
	global_load_dword v55, v[30:31], off nt
	v_lshl_add_u64 v[30:31], s[46:47], 2, v[28:29]
	s_mul_i32 s46, s0, 6
	global_load_dword v54, v[30:31], off nt
	v_lshl_add_u64 v[30:31], s[46:47], 2, v[28:29]
	s_mul_i32 s46, s0, 7
	global_load_dword v53, v[30:31], off nt
	v_lshl_add_u64 v[30:31], s[46:47], 2, v[28:29]
	s_lshl_b32 s46, s0, 3
	global_load_dword v84, v[30:31], off nt
	v_lshl_add_u64 v[30:31], s[46:47], 2, v[28:29]
	s_mul_i32 s46, s0, 9
	global_load_dword v71, v[30:31], off nt
	v_lshl_add_u64 v[30:31], s[46:47], 2, v[28:29]
	s_mul_i32 s46, s0, 10
	global_load_dword v83, v[30:31], off nt
	v_lshl_add_u64 v[30:31], s[46:47], 2, v[28:29]
	s_mul_i32 s46, s0, 11
	global_load_dword v52, v[30:31], off nt
	v_lshl_add_u64 v[30:31], s[46:47], 2, v[28:29]
	s_mul_i32 s46, s0, 12
	global_load_dword v51, v[30:31], off nt
	v_lshl_add_u64 v[30:31], s[46:47], 2, v[28:29]
	s_mul_i32 s46, s0, 13
	global_load_dword v50, v[30:31], off nt
	v_lshl_add_u64 v[30:31], s[46:47], 2, v[28:29]
	s_mul_i32 s46, s0, 14
	global_load_dword v49, v[30:31], off nt
	v_lshl_add_u64 v[30:31], s[46:47], 2, v[28:29]
	s_mul_i32 s46, s0, 15
	global_load_dword v48, v[30:31], off nt
	v_lshl_add_u64 v[30:31], s[46:47], 2, v[28:29]
	s_lshl_b32 s46, s0, 4
	global_load_dword v82, v[30:31], off nt
	v_lshl_add_u64 v[30:31], s[46:47], 2, v[28:29]
	s_mul_i32 s46, s0, 17
	global_load_dword v70, v[30:31], off nt
	v_lshl_add_u64 v[30:31], s[46:47], 2, v[28:29]
	s_mul_i32 s46, s0, 18
	global_load_dword v81, v[30:31], off nt
	v_lshl_add_u64 v[30:31], s[46:47], 2, v[28:29]
	s_mul_i32 s46, s0, 19
	global_load_dword v47, v[30:31], off nt
	v_lshl_add_u64 v[30:31], s[46:47], 2, v[28:29]
	s_mul_i32 s46, s0, 20
	global_load_dword v46, v[30:31], off nt
	v_lshl_add_u64 v[30:31], s[46:47], 2, v[28:29]
	s_mul_i32 s46, s0, 21
	global_load_dword v45, v[30:31], off nt
	v_lshl_add_u64 v[30:31], s[46:47], 2, v[28:29]
	s_mul_i32 s46, s0, 22
	global_load_dword v44, v[30:31], off nt
	v_lshl_add_u64 v[30:31], s[46:47], 2, v[28:29]
	s_mul_i32 s46, s0, 23
	global_load_dword v43, v[30:31], off nt
	v_lshl_add_u64 v[30:31], s[46:47], 2, v[28:29]
	s_mul_i32 s46, s0, 24
	global_load_dword v80, v[30:31], off nt
	v_lshl_add_u64 v[30:31], s[46:47], 2, v[28:29]
	s_mul_i32 s46, s0, 25
	global_load_dword v69, v[30:31], off nt
	v_lshl_add_u64 v[30:31], s[46:47], 2, v[28:29]
	s_mul_i32 s46, s0, 26
	global_load_dword v79, v[30:31], off nt
	v_lshl_add_u64 v[30:31], s[46:47], 2, v[28:29]
	s_mul_i32 s46, s0, 27
	global_load_dword v42, v[30:31], off nt
	v_lshl_add_u64 v[30:31], s[46:47], 2, v[28:29]
	s_mul_i32 s46, s0, 28
	global_load_dword v41, v[30:31], off nt
	v_lshl_add_u64 v[30:31], s[46:47], 2, v[28:29]
	s_mul_i32 s46, s0, 29
	global_load_dword v40, v[30:31], off nt
	v_lshl_add_u64 v[30:31], s[46:47], 2, v[28:29]
	s_mul_i32 s46, s0, 30
	global_load_dword v39, v[30:31], off nt
; __device__ __forceinline__ TrItem p0_item_of(const Params& p, int it, int lane) {
;     ...
;     t.dst = f8 ? (bf16*)((unsigned char*)WT + (size_t)n0 * K + k0) : WT + (size_t)n0 * K + k0; return t;
; __device__ __forceinline__ void tr_range(const Params& p, LAS unsigned char* lds, int first, int stride, int end, int lane, int wave) {
;     ...
;         if (more) { nxt = p0_item_of(p, it + stride, lane);
; #pragma unroll
;             for (int i = 0; i < 64; ++i) ra[i] = nxt.src[(size_t)i * nxt.N]; }
	v_lshl_add_u64 v[30:31], s[46:47], 2, v[28:29]
	s_mul_i32 s46, s0, 31
	global_load_dword v38, v[30:31], off nt
	v_lshl_add_u64 v[30:31], s[46:47], 2, v[28:29]
	s_lshl_b32 s46, s0, 5
	global_load_dword v78, v[30:31], off nt
	v_lshl_add_u64 v[30:31], s[46:47], 2, v[28:29]
	s_mul_i32 s46, s0, 33
	global_load_dword v68, v[30:31], off nt
	v_lshl_add_u64 v[30:31], s[46:47], 2, v[28:29]
	s_mul_i32 s46, s0, 34
	global_load_dword v77, v[30:31], off nt
	v_lshl_add_u64 v[30:31], s[46:47], 2, v[28:29]
	s_mul_i32 s46, s0, 35
	global_load_dword v37, v[30:31], off nt
	v_lshl_add_u64 v[30:31], s[46:47], 2, v[28:29]
	s_mul_i32 s46, s0, 36
	global_load_dword v36, v[30:31], off nt
	v_lshl_add_u64 v[30:31], s[46:47], 2, v[28:29]
	s_mul_i32 s46, s0, 37
	global_load_dword v35, v[30:31], off nt
	v_lshl_add_u64 v[30:31], s[46:47], 2, v[28:29]
	s_mul_i32 s46, s0, 38
	global_load_dword v34, v[30:31], off nt
	v_lshl_add_u64 v[30:31], s[46:47], 2, v[28:29]
	s_mul_i32 s46, s0, 39
	global_load_dword v33, v[30:31], off nt
	v_lshl_add_u64 v[30:31], s[46:47], 2, v[28:29]
	s_mul_i32 s46, s0, 40
	global_load_dword v76, v[30:31], off nt
	v_lshl_add_u64 v[30:31], s[46:47], 2, v[28:29]
	s_mul_i32 s46, s0, 41
	global_load_dword v67, v[30:31], off nt
	v_lshl_add_u64 v[30:31], s[46:47], 2, v[28:29]
	s_mul_i32 s46, s0, 42
	global_load_dword v75, v[30:31], off nt
	v_lshl_add_u64 v[30:31], s[46:47], 2, v[28:29]
	s_mul_i32 s46, s0, 43
	global_load_dword v32, v[30:31], off nt
	v_lshl_add_u64 v[30:31], s[46:47], 2, v[28:29]
	s_mul_i32 s46, s0, 44
	v_lshl_add_u64 v[60:61], s[46:47], 2, v[28:29]
	s_mul_i32 s46, s0, 45
	global_load_dword v31, v[30:31], off nt
	s_nop 0
	global_load_dword v30, v[60:61], off nt
	v_lshl_add_u64 v[60:61], s[46:47], 2, v[28:29]
	s_mul_i32 s46, s0, 46
	global_load_dword v27, v[60:61], off nt
	v_lshl_add_u64 v[60:61], s[46:47], 2, v[28:29]
	s_mul_i32 s46, s0, 47
	global_load_dword v25, v[60:61], off nt
	v_lshl_add_u64 v[60:61], s[46:47], 2, v[28:29]
	s_mul_i32 s46, s0, 48
	global_load_dword v74, v[60:61], off nt
	v_lshl_add_u64 v[60:61], s[46:47], 2, v[28:29]
	s_mul_i32 s46, s0, 49
	global_load_dword v66, v[60:61], off nt
	v_lshl_add_u64 v[60:61], s[46:47], 2, v[28:29]
	s_mul_i32 s46, s0, 50
	global_load_dword v73, v[60:61], off nt
	v_lshl_add_u64 v[60:61], s[46:47], 2, v[28:29]
	s_mul_i32 s46, s0, 51
	global_load_dword v23, v[60:61], off nt
	v_lshl_add_u64 v[60:61], s[46:47], 2, v[28:29]
	s_mul_i32 s46, s0, 52
	global_load_dword v21, v[60:61], off nt
	v_lshl_add_u64 v[60:61], s[46:47], 2, v[28:29]
	s_mul_i32 s46, s0, 53
	global_load_dword v19, v[60:61], off nt
	v_lshl_add_u64 v[60:61], s[46:47], 2, v[28:29]
	s_mul_i32 s46, s0, 54
	global_load_dword v17, v[60:61], off nt
	v_lshl_add_u64 v[60:61], s[46:47], 2, v[28:29]
	s_mul_i32 s46, s0, 55
	global_load_dword v15, v[60:61], off nt
	v_lshl_add_u64 v[60:61], s[46:47], 2, v[28:29]
	s_mul_i32 s46, s0, 56
	global_load_dword v72, v[60:61], off nt
	v_lshl_add_u64 v[60:61], s[46:47], 2, v[28:29]
	s_mul_i32 s46, s0, 57
	global_load_dword v65, v[60:61], off nt
	v_lshl_add_u64 v[60:61], s[46:47], 2, v[28:29]
	s_mul_i32 s46, s0, 58
	global_load_dword v64, v[60:61], off nt
	v_lshl_add_u64 v[60:61], s[46:47], 2, v[28:29]
	s_mul_i32 s46, s0, 59
	global_load_dword v63, v[60:61], off nt
	v_lshl_add_u64 v[60:61], s[46:47], 2, v[28:29]
	s_mul_i32 s46, s0, 60
	global_load_dword v62, v[60:61], off nt
	v_lshl_add_u64 v[60:61], s[46:47], 2, v[28:29]
	s_mul_i32 s46, s0, 61
	v_lshl_add_u64 v[86:87], s[46:47], 2, v[28:29]
	s_mul_i32 s46, s0, 62
	s_mul_i32 s0, s0, 63
	global_load_dword v61, v[60:61], off nt
	s_nop 0
	global_load_dword v60, v[86:87], off nt
	v_lshl_add_u64 v[86:87], s[46:47], 2, v[28:29]
	v_lshl_add_u64 v[28:29], s[0:1], 2, v[28:29]
	global_load_dword v59, v[86:87], off nt
	s_add_u32 s0, s48, s50
	global_load_dword v86, v[28:29], off nt
	s_addc_u32 s46, s49, s51
	s_and_b64 s[44:45], s[44:45], exec
	s_cselect_b32 s45, s57, s46
	s_cselect_b32 s44, s56, s0
